# v26 = v21 with MT4 k-loop global loads spread one per MFMA gap (8 in ks0, 4 in ks1)
# speedup vs baseline: 1.0057x; 1.0057x over previous
.LBB0_302:
	ds_read_b128 v[216:219], v176 offset:36864
	ds_read_b128 v[200:203], v188
	ds_read_b128 v[220:223], v176 offset:41472
	ds_read_b128 v[204:207], v188 offset:4608
	ds_read_b128 v[208:211], v188 offset:9216
	ds_read_b128 v[212:215], v187
	s_waitcnt lgkmcnt(4)
	v_mfma_f32_32x32x16_bf16 v[112:127], v[200:203], v[216:219], v[112:127]
	ds_read_b128 v[240:243], v176 offset:36896
	global_load_dwordx4 v[140:143], v190, s[42:43]
	s_waitcnt lgkmcnt(4)
	v_mfma_f32_32x32x16_bf16 v[96:111], v[200:203], v[220:223], v[96:111]
	ds_read_b128 v[224:227], v188 offset:32
	global_load_dwordx4 v[164:167], v190, s[40:41]
	s_waitcnt lgkmcnt(4)
	v_mfma_f32_32x32x16_bf16 v[80:95], v[204:207], v[216:219], v[80:95]
	ds_read_b128 v[244:247], v176 offset:41504
	global_load_dwordx4 v[128:131], v191, s[40:41]
	s_waitcnt lgkmcnt(5)
	v_mfma_f32_32x32x16_bf16 v[64:79], v[204:207], v[220:223], v[64:79]
	ds_read_b128 v[228:231], v188 offset:4640
	global_load_dwordx4 v[132:135], v192, s[40:41]
	s_waitcnt lgkmcnt(5)
	v_mfma_f32_32x32x16_bf16 v[48:63], v[208:211], v[216:219], v[48:63]
	ds_read_b128 v[232:235], v188 offset:9248
	global_load_dwordx4 v[136:139], v193, s[40:41]
	s_waitcnt lgkmcnt(6)
	v_mfma_f32_32x32x16_bf16 v[32:47], v[208:211], v[220:223], v[32:47]
	ds_read_b128 v[236:239], v187 offset:32
	global_load_dwordx4 v[144:147], v194, s[40:41]
	s_waitcnt lgkmcnt(6)
	v_mfma_f32_32x32x16_bf16 v[16:31], v[212:215], v[216:219], v[16:31]
	global_load_dwordx4 v[148:151], v195, s[40:41]
	s_waitcnt lgkmcnt(6)
	v_mfma_f32_32x32x16_bf16 v[0:15], v[212:215], v[220:223], v[0:15]
	global_load_dwordx4 v[152:155], v196, s[40:41]
	s_waitcnt lgkmcnt(4)
	v_mfma_f32_32x32x16_bf16 v[112:127], v[224:227], v[240:243], v[112:127]
	ds_read_b128 v[200:203], v188 offset:64
	global_load_dwordx4 v[156:159], v197, s[40:41]
	s_waitcnt lgkmcnt(4)
	v_mfma_f32_32x32x16_bf16 v[96:111], v[224:227], v[244:247], v[96:111]
	ds_read_b128 v[204:207], v188 offset:4672
	global_load_dwordx4 v[160:163], v191, s[42:43]
	s_waitcnt lgkmcnt(4)
	v_mfma_f32_32x32x16_bf16 v[80:95], v[228:231], v[240:243], v[80:95]
	ds_read_b128 v[208:211], v188 offset:9280
	global_load_dwordx4 v[168:171], v192, s[42:43]
	s_waitcnt lgkmcnt(5)
	v_mfma_f32_32x32x16_bf16 v[64:79], v[228:231], v[244:247], v[64:79]
	ds_read_b128 v[212:215], v187 offset:64
	global_load_dwordx4 v[172:175], v193, s[42:43]
	s_add_u32 s40, s40, 0x80
	s_addc_u32 s41, s41, 0
	s_add_u32 s42, s42, 0x80
	s_addc_u32 s43, s43, 0
	s_add_u32 s16, s16, 0x80
	s_waitcnt lgkmcnt(5)
	v_mfma_f32_32x32x16_bf16 v[48:63], v[232:235], v[240:243], v[48:63]
	ds_read_b128 v[216:219], v176 offset:36928
	s_waitcnt lgkmcnt(6)
	v_mfma_f32_32x32x16_bf16 v[32:47], v[232:235], v[244:247], v[32:47]
	ds_read_b128 v[220:223], v176 offset:41536
	s_waitcnt lgkmcnt(6)
	v_mfma_f32_32x32x16_bf16 v[16:31], v[236:239], v[240:243], v[16:31]
	s_waitcnt lgkmcnt(6)
	v_mfma_f32_32x32x16_bf16 v[0:15], v[236:239], v[244:247], v[0:15]
	s_waitcnt lgkmcnt(1)
	v_mfma_f32_32x32x16_bf16 v[112:127], v[200:203], v[216:219], v[112:127]
	ds_read_b128 v[224:227], v188 offset:96
	s_waitcnt lgkmcnt(1)
	v_mfma_f32_32x32x16_bf16 v[96:111], v[200:203], v[220:223], v[96:111]
	ds_read_b128 v[228:231], v188 offset:4704
	s_waitcnt lgkmcnt(3)
	v_mfma_f32_32x32x16_bf16 v[80:95], v[204:207], v[216:219], v[80:95]
	ds_read_b128 v[232:235], v188 offset:9312
	s_waitcnt lgkmcnt(3)
	v_mfma_f32_32x32x16_bf16 v[64:79], v[204:207], v[220:223], v[64:79]
	ds_read_b128 v[236:239], v187 offset:96
	s_waitcnt lgkmcnt(5)
	v_mfma_f32_32x32x16_bf16 v[48:63], v[208:211], v[216:219], v[48:63]
	ds_read_b128 v[240:243], v176 offset:36960
	s_waitcnt lgkmcnt(5)
	v_mfma_f32_32x32x16_bf16 v[32:47], v[208:211], v[220:223], v[32:47]
	ds_read_b128 v[244:247], v176 offset:41568
	s_waitcnt lgkmcnt(7)
	v_mfma_f32_32x32x16_bf16 v[16:31], v[212:215], v[216:219], v[16:31]
	s_waitcnt lgkmcnt(6)
	v_mfma_f32_32x32x16_bf16 v[0:15], v[212:215], v[220:223], v[0:15]
	s_waitcnt lgkmcnt(0)
	s_barrier
	s_waitcnt vmcnt(0)
	s_waitcnt lgkmcnt(1)
	v_mfma_f32_32x32x16_bf16 v[112:127], v[224:227], v[240:243], v[112:127]
	ds_write_b128 v189, v[164:167]
	ds_write_b128 v189, v[128:131] offset:4608
	s_waitcnt lgkmcnt(2)
	v_mfma_f32_32x32x16_bf16 v[96:111], v[224:227], v[244:247], v[96:111]
	ds_write_b128 v189, v[132:135] offset:9216
	s_waitcnt lgkmcnt(4)
	v_mfma_f32_32x32x16_bf16 v[80:95], v[228:231], v[240:243], v[80:95]
	ds_write_b128 v189, v[136:139] offset:13824
	ds_write_b128 v189, v[144:147] offset:18432
	s_waitcnt lgkmcnt(5)
	v_mfma_f32_32x32x16_bf16 v[64:79], v[228:231], v[244:247], v[64:79]
	ds_write_b128 v189, v[148:151] offset:23040
	s_waitcnt lgkmcnt(7)
	v_mfma_f32_32x32x16_bf16 v[48:63], v[232:235], v[240:243], v[48:63]
	ds_write_b128 v189, v[152:155] offset:27648
	ds_write_b128 v189, v[156:159] offset:32256
	s_waitcnt lgkmcnt(8)
	v_mfma_f32_32x32x16_bf16 v[32:47], v[232:235], v[244:247], v[32:47]
	ds_write_b128 v189, v[140:143] offset:36864
	s_waitcnt lgkmcnt(10)
	v_mfma_f32_32x32x16_bf16 v[16:31], v[236:239], v[240:243], v[16:31]
	ds_write_b128 v189, v[160:163] offset:41472
	ds_write_b128 v189, v[168:171] offset:46080
	s_waitcnt lgkmcnt(11)
	v_mfma_f32_32x32x16_bf16 v[0:15], v[236:239], v[244:247], v[0:15]
	ds_write_b128 v189, v[172:175] offset:50688
	s_waitcnt lgkmcnt(0)
	s_barrier
	s_cmpk_lg_i32 s16, 0x780
	s_cbranch_scc1 .LBB0_302
	ds_read_b128 v[216:219], v176 offset:36864
	ds_read_b128 v[200:203], v188
	ds_read_b128 v[220:223], v176 offset:41472
	ds_read_b128 v[204:207], v188 offset:4608
	ds_read_b128 v[208:211], v188 offset:9216
	ds_read_b128 v[212:215], v187
	s_waitcnt lgkmcnt(4)
	v_mfma_f32_32x32x16_bf16 v[112:127], v[200:203], v[216:219], v[112:127]
	ds_read_b128 v[240:243], v176 offset:36896
	s_waitcnt lgkmcnt(4)
	v_mfma_f32_32x32x16_bf16 v[96:111], v[200:203], v[220:223], v[96:111]
	ds_read_b128 v[224:227], v188 offset:32
	s_waitcnt lgkmcnt(4)
	v_mfma_f32_32x32x16_bf16 v[80:95], v[204:207], v[216:219], v[80:95]
	ds_read_b128 v[244:247], v176 offset:41504
	s_waitcnt lgkmcnt(5)
	v_mfma_f32_32x32x16_bf16 v[64:79], v[204:207], v[220:223], v[64:79]
	ds_read_b128 v[228:231], v188 offset:4640
	s_waitcnt lgkmcnt(5)
	v_mfma_f32_32x32x16_bf16 v[48:63], v[208:211], v[216:219], v[48:63]
	ds_read_b128 v[232:235], v188 offset:9248
	s_waitcnt lgkmcnt(6)
	v_mfma_f32_32x32x16_bf16 v[32:47], v[208:211], v[220:223], v[32:47]
	ds_read_b128 v[236:239], v187 offset:32
	s_waitcnt lgkmcnt(6)
	v_mfma_f32_32x32x16_bf16 v[16:31], v[212:215], v[216:219], v[16:31]
	s_waitcnt lgkmcnt(6)
	v_mfma_f32_32x32x16_bf16 v[0:15], v[212:215], v[220:223], v[0:15]
	s_waitcnt lgkmcnt(4)
	v_mfma_f32_32x32x16_bf16 v[112:127], v[224:227], v[240:243], v[112:127]
	ds_read_b128 v[200:203], v188 offset:64
	s_waitcnt lgkmcnt(4)
	v_mfma_f32_32x32x16_bf16 v[96:111], v[224:227], v[244:247], v[96:111]
	ds_read_b128 v[204:207], v188 offset:4672
	s_waitcnt lgkmcnt(4)
	v_mfma_f32_32x32x16_bf16 v[80:95], v[228:231], v[240:243], v[80:95]
	ds_read_b128 v[208:211], v188 offset:9280
	s_waitcnt lgkmcnt(5)
	v_mfma_f32_32x32x16_bf16 v[64:79], v[228:231], v[244:247], v[64:79]
	ds_read_b128 v[212:215], v187 offset:64
	s_waitcnt lgkmcnt(5)
	v_mfma_f32_32x32x16_bf16 v[48:63], v[232:235], v[240:243], v[48:63]
	ds_read_b128 v[216:219], v176 offset:36928
	s_waitcnt lgkmcnt(6)
	v_mfma_f32_32x32x16_bf16 v[32:47], v[232:235], v[244:247], v[32:47]
	ds_read_b128 v[220:223], v176 offset:41536
	s_waitcnt lgkmcnt(6)
	v_mfma_f32_32x32x16_bf16 v[16:31], v[236:239], v[240:243], v[16:31]
	s_waitcnt lgkmcnt(6)
	v_mfma_f32_32x32x16_bf16 v[0:15], v[236:239], v[244:247], v[0:15]
	s_waitcnt lgkmcnt(1)
	v_mfma_f32_32x32x16_bf16 v[112:127], v[200:203], v[216:219], v[112:127]
	ds_read_b128 v[224:227], v188 offset:96
	s_waitcnt lgkmcnt(1)
	v_mfma_f32_32x32x16_bf16 v[96:111], v[200:203], v[220:223], v[96:111]
	ds_read_b128 v[228:231], v188 offset:4704
	s_waitcnt lgkmcnt(3)
	v_mfma_f32_32x32x16_bf16 v[80:95], v[204:207], v[216:219], v[80:95]
	ds_read_b128 v[232:235], v188 offset:9312
	s_waitcnt lgkmcnt(3)
	v_mfma_f32_32x32x16_bf16 v[64:79], v[204:207], v[220:223], v[64:79]
	ds_read_b128 v[236:239], v187 offset:96
	s_waitcnt lgkmcnt(5)
	v_mfma_f32_32x32x16_bf16 v[48:63], v[208:211], v[216:219], v[48:63]
	ds_read_b128 v[240:243], v176 offset:36960
	s_waitcnt lgkmcnt(5)
	v_mfma_f32_32x32x16_bf16 v[32:47], v[208:211], v[220:223], v[32:47]
	ds_read_b128 v[244:247], v176 offset:41568
	s_waitcnt lgkmcnt(7)
	v_mfma_f32_32x32x16_bf16 v[16:31], v[212:215], v[216:219], v[16:31]
	s_waitcnt lgkmcnt(6)
	v_mfma_f32_32x32x16_bf16 v[0:15], v[212:215], v[220:223], v[0:15]
	s_waitcnt lgkmcnt(1)
	v_mfma_f32_32x32x16_bf16 v[112:127], v[224:227], v[240:243], v[112:127]
	s_waitcnt lgkmcnt(0)
	v_mfma_f32_32x32x16_bf16 v[96:111], v[224:227], v[244:247], v[96:111]
	s_waitcnt lgkmcnt(1)
	v_mfma_f32_32x32x16_bf16 v[80:95], v[228:231], v[240:243], v[80:95]
	s_waitcnt lgkmcnt(0)
	v_mfma_f32_32x32x16_bf16 v[64:79], v[228:231], v[244:247], v[64:79]
	s_waitcnt lgkmcnt(1)
	v_mfma_f32_32x32x16_bf16 v[48:63], v[232:235], v[240:243], v[48:63]
	s_waitcnt lgkmcnt(0)
	v_mfma_f32_32x32x16_bf16 v[32:47], v[232:235], v[244:247], v[32:47]
	s_waitcnt lgkmcnt(1)
	v_mfma_f32_32x32x16_bf16 v[16:31], v[236:239], v[240:243], v[16:31]
	s_waitcnt lgkmcnt(0)
	v_mfma_f32_32x32x16_bf16 v[0:15], v[236:239], v[244:247], v[0:15]
	s_mul_i32 s44, s12, 0x1240
	s_add_u32 s40, s30, s44
	s_addc_u32 s41, s31, 0
	s_lshl_b32 s44, s8, 1
	s_add_u32 s40, s40, s44
	s_addc_u32 s41, s41, 0
	s_add_u32 s40, s40, 0x7157900
	s_addc_u32 s41, s41, 0
	v_and_b32_e32 v131, 15, v182
	v_lshrrev_b32_e32 v172, 4, v182
	v_lshl_add_u32 v130, v131, 3, s8
	s_movk_i32 s44, 0x920
	v_cmp_gt_u32_e64 s[42:43], s44, v130
	v_mul_u32_u24_e32 v164, 0x1240, v172
	v_lshl_add_u32 v164, v131, 4, v164
	v_add_u32_e32 v165, 0x12400, v164
	v_add_u32_e32 v166, 0x24800, v164
	v_add_u32_e32 v167, 0x36c00, v164
	v_add_u32_e32 v168, 0x92000, v164
	v_add_u32_e32 v169, 0xa4400, v164
	v_add_u32_e32 v170, 0xb6800, v164
	v_add_u32_e32 v171, 0xc8c00, v164
	v_mul_u32_u24_e32 v129, 0x110, v172
	v_lshl_add_u32 v129, v131, 4, v129
	v_lshrrev_b32_e32 v131, 7, v182
	v_bfe_u32 v172, v182, 5, 1
	v_lshlrev_b32_e32 v131, 6, v131
	v_lshl_or_b32 v131, v172, 2, v131
	v_mul_u32_u24_e32 v131, 136, v131
	v_and_b32_e32 v172, 0x5f, v182
	v_add_lshl_u32 v128, v131, v172, 1
	s_barrier
	v_cvt_pk_bf16_f32 v112, v112, v113
	v_cvt_pk_bf16_f32 v114, v114, v115
	v_cvt_pk_bf16_f32 v116, v116, v117
	v_cvt_pk_bf16_f32 v118, v118, v119
	v_cvt_pk_bf16_f32 v120, v120, v121
	v_cvt_pk_bf16_f32 v122, v122, v123
	v_cvt_pk_bf16_f32 v124, v124, v125
	v_cvt_pk_bf16_f32 v126, v126, v127
	v_cvt_pk_bf16_f32 v96, v96, v97
	v_cvt_pk_bf16_f32 v98, v98, v99
	v_cvt_pk_bf16_f32 v100, v100, v101
	v_cvt_pk_bf16_f32 v102, v102, v103
	v_cvt_pk_bf16_f32 v104, v104, v105
	v_cvt_pk_bf16_f32 v106, v106, v107
	v_cvt_pk_bf16_f32 v108, v108, v109
	v_cvt_pk_bf16_f32 v110, v110, v111
	v_cvt_pk_bf16_f32 v80, v80, v81
	v_cvt_pk_bf16_f32 v82, v82, v83
	v_cvt_pk_bf16_f32 v84, v84, v85
	v_cvt_pk_bf16_f32 v86, v86, v87
	v_cvt_pk_bf16_f32 v88, v88, v89
	v_cvt_pk_bf16_f32 v90, v90, v91
	v_cvt_pk_bf16_f32 v92, v92, v93
	v_cvt_pk_bf16_f32 v94, v94, v95
	v_cvt_pk_bf16_f32 v64, v64, v65
	v_cvt_pk_bf16_f32 v66, v66, v67
	v_cvt_pk_bf16_f32 v68, v68, v69
	v_cvt_pk_bf16_f32 v70, v70, v71
	v_cvt_pk_bf16_f32 v72, v72, v73
	v_cvt_pk_bf16_f32 v74, v74, v75
	v_cvt_pk_bf16_f32 v76, v76, v77
	v_cvt_pk_bf16_f32 v78, v78, v79
	ds_write_b16 v128, v112
	ds_write_b16_d16_hi v128, v112 offset:272
	ds_write_b16 v128, v114 offset:544
	ds_write_b16_d16_hi v128, v114 offset:816
	ds_write_b16 v128, v116 offset:2176
	ds_write_b16_d16_hi v128, v116 offset:2448
	ds_write_b16 v128, v118 offset:2720
	ds_write_b16_d16_hi v128, v118 offset:2992
	ds_write_b16 v128, v120 offset:4352
	ds_write_b16_d16_hi v128, v120 offset:4624
	ds_write_b16 v128, v122 offset:4896
	ds_write_b16_d16_hi v128, v122 offset:5168
	ds_write_b16 v128, v124 offset:6528
	ds_write_b16_d16_hi v128, v124 offset:6800
	ds_write_b16 v128, v126 offset:7072
	ds_write_b16_d16_hi v128, v126 offset:7344
	ds_write_b16 v128, v96 offset:64
	ds_write_b16_d16_hi v128, v96 offset:336
	ds_write_b16 v128, v98 offset:608
	ds_write_b16_d16_hi v128, v98 offset:880
	ds_write_b16 v128, v100 offset:2240
	ds_write_b16_d16_hi v128, v100 offset:2512
	ds_write_b16 v128, v102 offset:2784
	ds_write_b16_d16_hi v128, v102 offset:3056
	ds_write_b16 v128, v104 offset:4416
	ds_write_b16_d16_hi v128, v104 offset:4688
	ds_write_b16 v128, v106 offset:4960
	ds_write_b16_d16_hi v128, v106 offset:5232
	ds_write_b16 v128, v108 offset:6592
	ds_write_b16_d16_hi v128, v108 offset:6864
	ds_write_b16 v128, v110 offset:7136
	ds_write_b16_d16_hi v128, v110 offset:7408
	ds_write_b16 v128, v80 offset:8704
	ds_write_b16_d16_hi v128, v80 offset:8976
	ds_write_b16 v128, v82 offset:9248
	ds_write_b16_d16_hi v128, v82 offset:9520
	ds_write_b16 v128, v84 offset:10880
	ds_write_b16_d16_hi v128, v84 offset:11152
	ds_write_b16 v128, v86 offset:11424
	ds_write_b16_d16_hi v128, v86 offset:11696
	ds_write_b16 v128, v88 offset:13056
	ds_write_b16_d16_hi v128, v88 offset:13328
	ds_write_b16 v128, v90 offset:13600
	ds_write_b16_d16_hi v128, v90 offset:13872
	ds_write_b16 v128, v92 offset:15232
	ds_write_b16_d16_hi v128, v92 offset:15504
	ds_write_b16 v128, v94 offset:15776
	ds_write_b16_d16_hi v128, v94 offset:16048
	ds_write_b16 v128, v64 offset:8768
	ds_write_b16_d16_hi v128, v64 offset:9040
	ds_write_b16 v128, v66 offset:9312
	ds_write_b16_d16_hi v128, v66 offset:9584
	ds_write_b16 v128, v68 offset:10944
	ds_write_b16_d16_hi v128, v68 offset:11216
	ds_write_b16 v128, v70 offset:11488
	ds_write_b16_d16_hi v128, v70 offset:11760
	ds_write_b16 v128, v72 offset:13120
	ds_write_b16_d16_hi v128, v72 offset:13392
	ds_write_b16 v128, v74 offset:13664
	ds_write_b16_d16_hi v128, v74 offset:13936
	ds_write_b16 v128, v76 offset:15296
	ds_write_b16_d16_hi v128, v76 offset:15568
	ds_write_b16 v128, v78 offset:15840
	ds_write_b16_d16_hi v128, v78 offset:16112
	s_waitcnt lgkmcnt(0)
	s_barrier
	ds_read_b128 v[132:135], v129
	ds_read_b128 v[136:139], v129 offset:4352
	ds_read_b128 v[140:143], v129 offset:8704
	ds_read_b128 v[144:147], v129 offset:13056
	ds_read_b128 v[148:151], v129 offset:17408
	ds_read_b128 v[152:155], v129 offset:21760
	ds_read_b128 v[156:159], v129 offset:26112
	ds_read_b128 v[160:163], v129 offset:30464
	v_cvt_pk_bf16_f32 v48, v48, v49
	v_cvt_pk_bf16_f32 v50, v50, v51
	v_cvt_pk_bf16_f32 v52, v52, v53
	v_cvt_pk_bf16_f32 v54, v54, v55
	v_cvt_pk_bf16_f32 v56, v56, v57
	v_cvt_pk_bf16_f32 v58, v58, v59
	v_cvt_pk_bf16_f32 v60, v60, v61
	v_cvt_pk_bf16_f32 v62, v62, v63
	v_cvt_pk_bf16_f32 v32, v32, v33
	v_cvt_pk_bf16_f32 v34, v34, v35
	v_cvt_pk_bf16_f32 v36, v36, v37
	v_cvt_pk_bf16_f32 v38, v38, v39
	v_cvt_pk_bf16_f32 v40, v40, v41
	v_cvt_pk_bf16_f32 v42, v42, v43
	v_cvt_pk_bf16_f32 v44, v44, v45
	v_cvt_pk_bf16_f32 v46, v46, v47
	v_cvt_pk_bf16_f32 v16, v16, v17
	v_cvt_pk_bf16_f32 v18, v18, v19
	v_cvt_pk_bf16_f32 v20, v20, v21
	v_cvt_pk_bf16_f32 v22, v22, v23
	v_cvt_pk_bf16_f32 v24, v24, v25
	v_cvt_pk_bf16_f32 v26, v26, v27
	v_cvt_pk_bf16_f32 v28, v28, v29
	v_cvt_pk_bf16_f32 v30, v30, v31
	v_cvt_pk_bf16_f32 v0, v0, v1
	v_cvt_pk_bf16_f32 v2, v2, v3
	v_cvt_pk_bf16_f32 v4, v4, v5
	v_cvt_pk_bf16_f32 v6, v6, v7
	v_cvt_pk_bf16_f32 v8, v8, v9
	v_cvt_pk_bf16_f32 v10, v10, v11
	v_cvt_pk_bf16_f32 v12, v12, v13
	v_cvt_pk_bf16_f32 v14, v14, v15
	s_and_saveexec_b64 s[46:47], s[42:43]
	s_waitcnt lgkmcnt(7)
	global_store_dwordx4 v164, v[132:135], s[40:41]
	s_waitcnt lgkmcnt(6)
	global_store_dwordx4 v165, v[136:139], s[40:41]
	s_waitcnt lgkmcnt(5)
	global_store_dwordx4 v166, v[140:143], s[40:41]
	s_waitcnt lgkmcnt(4)
	global_store_dwordx4 v167, v[144:147], s[40:41]
	s_waitcnt lgkmcnt(3)
	global_store_dwordx4 v168, v[148:151], s[40:41]
	s_waitcnt lgkmcnt(2)
	global_store_dwordx4 v169, v[152:155], s[40:41]
	s_waitcnt lgkmcnt(1)
	global_store_dwordx4 v170, v[156:159], s[40:41]
	s_waitcnt lgkmcnt(0)
	global_store_dwordx4 v171, v[160:163], s[40:41]
	s_or_b64 exec, exec, s[46:47]
	s_barrier
	ds_write_b16 v128, v48
	ds_write_b16_d16_hi v128, v48 offset:272
	ds_write_b16 v128, v50 offset:544
	ds_write_b16_d16_hi v128, v50 offset:816
	ds_write_b16 v128, v52 offset:2176
	ds_write_b16_d16_hi v128, v52 offset:2448
	ds_write_b16 v128, v54 offset:2720
	ds_write_b16_d16_hi v128, v54 offset:2992
	ds_write_b16 v128, v56 offset:4352
	ds_write_b16_d16_hi v128, v56 offset:4624
	ds_write_b16 v128, v58 offset:4896
	ds_write_b16_d16_hi v128, v58 offset:5168
	ds_write_b16 v128, v60 offset:6528
	ds_write_b16_d16_hi v128, v60 offset:6800
	ds_write_b16 v128, v62 offset:7072
	ds_write_b16_d16_hi v128, v62 offset:7344
	ds_write_b16 v128, v32 offset:64
	ds_write_b16_d16_hi v128, v32 offset:336
	ds_write_b16 v128, v34 offset:608
	ds_write_b16_d16_hi v128, v34 offset:880
	ds_write_b16 v128, v36 offset:2240
	ds_write_b16_d16_hi v128, v36 offset:2512
	ds_write_b16 v128, v38 offset:2784
	ds_write_b16_d16_hi v128, v38 offset:3056
	ds_write_b16 v128, v40 offset:4416
	ds_write_b16_d16_hi v128, v40 offset:4688
	ds_write_b16 v128, v42 offset:4960
	ds_write_b16_d16_hi v128, v42 offset:5232
	ds_write_b16 v128, v44 offset:6592
	ds_write_b16_d16_hi v128, v44 offset:6864
	ds_write_b16 v128, v46 offset:7136
	ds_write_b16_d16_hi v128, v46 offset:7408
	ds_write_b16 v128, v16 offset:8704
	ds_write_b16_d16_hi v128, v16 offset:8976
	ds_write_b16 v128, v18 offset:9248
	ds_write_b16_d16_hi v128, v18 offset:9520
	ds_write_b16 v128, v20 offset:10880
	ds_write_b16_d16_hi v128, v20 offset:11152
	ds_write_b16 v128, v22 offset:11424
	ds_write_b16_d16_hi v128, v22 offset:11696
	ds_write_b16 v128, v24 offset:13056
	ds_write_b16_d16_hi v128, v24 offset:13328
	ds_write_b16 v128, v26 offset:13600
	ds_write_b16_d16_hi v128, v26 offset:13872
	ds_write_b16 v128, v28 offset:15232
	ds_write_b16_d16_hi v128, v28 offset:15504
	ds_write_b16 v128, v30 offset:15776
	ds_write_b16_d16_hi v128, v30 offset:16048
	ds_write_b16 v128, v0 offset:8768
	ds_write_b16_d16_hi v128, v0 offset:9040
	ds_write_b16 v128, v2 offset:9312
	ds_write_b16_d16_hi v128, v2 offset:9584
	ds_write_b16 v128, v4 offset:10944
	ds_write_b16_d16_hi v128, v4 offset:11216
	ds_write_b16 v128, v6 offset:11488
	ds_write_b16_d16_hi v128, v6 offset:11760
	ds_write_b16 v128, v8 offset:13120
	ds_write_b16_d16_hi v128, v8 offset:13392
	ds_write_b16 v128, v10 offset:13664
	ds_write_b16_d16_hi v128, v10 offset:13936
	ds_write_b16 v128, v12 offset:15296
	ds_write_b16_d16_hi v128, v12 offset:15568
	ds_write_b16 v128, v14 offset:15840
	ds_write_b16_d16_hi v128, v14 offset:16112
	s_waitcnt lgkmcnt(0)
	s_barrier
	ds_read_b128 v[132:135], v129
	ds_read_b128 v[136:139], v129 offset:4352
	ds_read_b128 v[140:143], v129 offset:8704
	ds_read_b128 v[144:147], v129 offset:13056
	ds_read_b128 v[148:151], v129 offset:17408
	ds_read_b128 v[152:155], v129 offset:21760
	ds_read_b128 v[156:159], v129 offset:26112
	ds_read_b128 v[160:163], v129 offset:30464
	v_add_u32_e32 v164, 0x49000, v164
	v_add_u32_e32 v165, 0x49000, v165
	v_add_u32_e32 v166, 0x49000, v166
	v_add_u32_e32 v167, 0x49000, v167
	v_add_u32_e32 v168, 0x49000, v168
	v_add_u32_e32 v169, 0x49000, v169
	v_add_u32_e32 v170, 0x49000, v170
	v_add_u32_e32 v171, 0x49000, v171
	s_and_saveexec_b64 s[46:47], s[42:43]
	s_waitcnt lgkmcnt(7)
	global_store_dwordx4 v164, v[132:135], s[40:41]
	s_waitcnt lgkmcnt(6)
	global_store_dwordx4 v165, v[136:139], s[40:41]
	s_waitcnt lgkmcnt(5)
	global_store_dwordx4 v166, v[140:143], s[40:41]
	s_waitcnt lgkmcnt(4)
	global_store_dwordx4 v167, v[144:147], s[40:41]
	s_waitcnt lgkmcnt(3)
	global_store_dwordx4 v168, v[148:151], s[40:41]
	s_waitcnt lgkmcnt(2)
	global_store_dwordx4 v169, v[152:155], s[40:41]
	s_waitcnt lgkmcnt(1)
	global_store_dwordx4 v170, v[156:159], s[40:41]
	s_waitcnt lgkmcnt(0)
	global_store_dwordx4 v171, v[160:163], s[40:41]
	s_or_b64 exec, exec, s[46:47]
	s_branch .Lmt4_tail_0

.LBB0_997:
	ds_read_b128 v[216:219], v188 offset:36864
	ds_read_b128 v[200:203], v187
	ds_read_b128 v[220:223], v188 offset:41472
	ds_read_b128 v[204:207], v187 offset:4608
	ds_read_b128 v[208:211], v187 offset:9216
	ds_read_b128 v[212:215], v176
	s_waitcnt lgkmcnt(4)
	v_mfma_f32_32x32x16_bf16 v[112:127], v[200:203], v[216:219], v[112:127]
	ds_read_b128 v[240:243], v188 offset:36896
	global_load_dwordx4 v[160:163], v190, s[38:39]
	s_waitcnt lgkmcnt(4)
	v_mfma_f32_32x32x16_bf16 v[96:111], v[200:203], v[220:223], v[96:111]
	ds_read_b128 v[224:227], v187 offset:32
	global_load_dwordx4 v[128:131], v191, s[38:39]
	s_waitcnt lgkmcnt(4)
	v_mfma_f32_32x32x16_bf16 v[80:95], v[204:207], v[216:219], v[80:95]
	ds_read_b128 v[244:247], v188 offset:41504
	global_load_dwordx4 v[132:135], v192, s[38:39]
	s_waitcnt lgkmcnt(5)
	v_mfma_f32_32x32x16_bf16 v[64:79], v[204:207], v[220:223], v[64:79]
	ds_read_b128 v[228:231], v187 offset:4640
	global_load_dwordx4 v[136:139], v193, s[38:39]
	s_waitcnt lgkmcnt(5)
	v_mfma_f32_32x32x16_bf16 v[48:63], v[208:211], v[216:219], v[48:63]
	ds_read_b128 v[232:235], v187 offset:9248
	global_load_dwordx4 v[140:143], v194, s[38:39]
	s_waitcnt lgkmcnt(6)
	v_mfma_f32_32x32x16_bf16 v[32:47], v[208:211], v[220:223], v[32:47]
	ds_read_b128 v[236:239], v176 offset:32
	global_load_dwordx4 v[144:147], v195, s[38:39]
	s_waitcnt lgkmcnt(6)
	v_mfma_f32_32x32x16_bf16 v[16:31], v[212:215], v[216:219], v[16:31]
	global_load_dwordx4 v[148:151], v196, s[38:39]
	s_waitcnt lgkmcnt(6)
	v_mfma_f32_32x32x16_bf16 v[0:15], v[212:215], v[220:223], v[0:15]
	global_load_dwordx4 v[156:159], v197, s[38:39]
	s_waitcnt lgkmcnt(4)
	v_mfma_f32_32x32x16_bf16 v[112:127], v[224:227], v[240:243], v[112:127]
	ds_read_b128 v[200:203], v187 offset:64
	global_load_dwordx4 v[152:155], v190, s[40:41]
	s_waitcnt lgkmcnt(4)
	v_mfma_f32_32x32x16_bf16 v[96:111], v[224:227], v[244:247], v[96:111]
	ds_read_b128 v[204:207], v187 offset:4672
	global_load_dwordx4 v[164:167], v191, s[40:41]
	s_waitcnt lgkmcnt(4)
	v_mfma_f32_32x32x16_bf16 v[80:95], v[228:231], v[240:243], v[80:95]
	ds_read_b128 v[208:211], v187 offset:9280
	global_load_dwordx4 v[168:171], v192, s[40:41]
	s_waitcnt lgkmcnt(5)
	v_mfma_f32_32x32x16_bf16 v[64:79], v[228:231], v[244:247], v[64:79]
	ds_read_b128 v[212:215], v176 offset:64
	global_load_dwordx4 v[172:175], v193, s[40:41]
	s_add_u32 s38, s38, 0x80
	s_addc_u32 s39, s39, 0
	s_add_u32 s40, s40, 0x80
	s_addc_u32 s41, s41, 0
	s_add_u32 s12, s12, 0x80
	s_waitcnt lgkmcnt(5)
	v_mfma_f32_32x32x16_bf16 v[48:63], v[232:235], v[240:243], v[48:63]
	ds_read_b128 v[216:219], v188 offset:36928
	s_waitcnt lgkmcnt(6)
	v_mfma_f32_32x32x16_bf16 v[32:47], v[232:235], v[244:247], v[32:47]
	ds_read_b128 v[220:223], v188 offset:41536
	s_waitcnt lgkmcnt(6)
	v_mfma_f32_32x32x16_bf16 v[16:31], v[236:239], v[240:243], v[16:31]
	s_waitcnt lgkmcnt(6)
	v_mfma_f32_32x32x16_bf16 v[0:15], v[236:239], v[244:247], v[0:15]
	s_waitcnt lgkmcnt(1)
	v_mfma_f32_32x32x16_bf16 v[112:127], v[200:203], v[216:219], v[112:127]
	ds_read_b128 v[224:227], v187 offset:96
	s_waitcnt lgkmcnt(1)
	v_mfma_f32_32x32x16_bf16 v[96:111], v[200:203], v[220:223], v[96:111]
	ds_read_b128 v[228:231], v187 offset:4704
	s_waitcnt lgkmcnt(3)
	v_mfma_f32_32x32x16_bf16 v[80:95], v[204:207], v[216:219], v[80:95]
	ds_read_b128 v[232:235], v187 offset:9312
	s_waitcnt lgkmcnt(3)
	v_mfma_f32_32x32x16_bf16 v[64:79], v[204:207], v[220:223], v[64:79]
	ds_read_b128 v[236:239], v176 offset:96
	s_waitcnt lgkmcnt(5)
	v_mfma_f32_32x32x16_bf16 v[48:63], v[208:211], v[216:219], v[48:63]
	ds_read_b128 v[240:243], v188 offset:36960
	s_waitcnt lgkmcnt(5)
	v_mfma_f32_32x32x16_bf16 v[32:47], v[208:211], v[220:223], v[32:47]
	ds_read_b128 v[244:247], v188 offset:41568
	s_waitcnt lgkmcnt(7)
	v_mfma_f32_32x32x16_bf16 v[16:31], v[212:215], v[216:219], v[16:31]
	s_waitcnt lgkmcnt(6)
	v_mfma_f32_32x32x16_bf16 v[0:15], v[212:215], v[220:223], v[0:15]
	s_waitcnt lgkmcnt(0)
	s_barrier
	s_waitcnt vmcnt(0)
	s_waitcnt lgkmcnt(1)
	v_mfma_f32_32x32x16_bf16 v[112:127], v[224:227], v[240:243], v[112:127]
	ds_write_b128 v189, v[160:163]
	ds_write_b128 v189, v[128:131] offset:4608
	s_waitcnt lgkmcnt(2)
	v_mfma_f32_32x32x16_bf16 v[96:111], v[224:227], v[244:247], v[96:111]
	ds_write_b128 v189, v[132:135] offset:9216
	s_waitcnt lgkmcnt(4)
	v_mfma_f32_32x32x16_bf16 v[80:95], v[228:231], v[240:243], v[80:95]
	ds_write_b128 v189, v[136:139] offset:13824
	ds_write_b128 v189, v[140:143] offset:18432
	s_waitcnt lgkmcnt(5)
	v_mfma_f32_32x32x16_bf16 v[64:79], v[228:231], v[244:247], v[64:79]
	ds_write_b128 v189, v[144:147] offset:23040
	s_waitcnt lgkmcnt(7)
	v_mfma_f32_32x32x16_bf16 v[48:63], v[232:235], v[240:243], v[48:63]
	ds_write_b128 v189, v[148:151] offset:27648
	ds_write_b128 v189, v[156:159] offset:32256
	s_waitcnt lgkmcnt(8)
	v_mfma_f32_32x32x16_bf16 v[32:47], v[232:235], v[244:247], v[32:47]
	ds_write_b128 v189, v[152:155] offset:36864
	s_waitcnt lgkmcnt(10)
	v_mfma_f32_32x32x16_bf16 v[16:31], v[236:239], v[240:243], v[16:31]
	ds_write_b128 v189, v[164:167] offset:41472
	ds_write_b128 v189, v[168:171] offset:46080
	s_waitcnt lgkmcnt(11)
	v_mfma_f32_32x32x16_bf16 v[0:15], v[236:239], v[244:247], v[0:15]
	ds_write_b128 v189, v[172:175] offset:50688
	s_waitcnt lgkmcnt(0)
	s_barrier
	s_cmpk_lg_i32 s12, 0x780
	s_cbranch_scc1 .LBB0_997
	ds_read_b128 v[216:219], v188 offset:36864
	ds_read_b128 v[200:203], v187
	ds_read_b128 v[220:223], v188 offset:41472
	ds_read_b128 v[204:207], v187 offset:4608
	ds_read_b128 v[208:211], v187 offset:9216
	ds_read_b128 v[212:215], v176
	s_waitcnt lgkmcnt(4)
	v_mfma_f32_32x32x16_bf16 v[112:127], v[200:203], v[216:219], v[112:127]
	ds_read_b128 v[240:243], v188 offset:36896
	s_waitcnt lgkmcnt(4)
	v_mfma_f32_32x32x16_bf16 v[96:111], v[200:203], v[220:223], v[96:111]
	ds_read_b128 v[224:227], v187 offset:32
	s_waitcnt lgkmcnt(4)
	v_mfma_f32_32x32x16_bf16 v[80:95], v[204:207], v[216:219], v[80:95]
	ds_read_b128 v[244:247], v188 offset:41504
	s_waitcnt lgkmcnt(5)
	v_mfma_f32_32x32x16_bf16 v[64:79], v[204:207], v[220:223], v[64:79]
	ds_read_b128 v[228:231], v187 offset:4640
	s_waitcnt lgkmcnt(5)
	v_mfma_f32_32x32x16_bf16 v[48:63], v[208:211], v[216:219], v[48:63]
	ds_read_b128 v[232:235], v187 offset:9248
	s_waitcnt lgkmcnt(6)
	v_mfma_f32_32x32x16_bf16 v[32:47], v[208:211], v[220:223], v[32:47]
	ds_read_b128 v[236:239], v176 offset:32
	s_waitcnt lgkmcnt(6)
	v_mfma_f32_32x32x16_bf16 v[16:31], v[212:215], v[216:219], v[16:31]
	s_waitcnt lgkmcnt(6)
	v_mfma_f32_32x32x16_bf16 v[0:15], v[212:215], v[220:223], v[0:15]
	s_waitcnt lgkmcnt(4)
	v_mfma_f32_32x32x16_bf16 v[112:127], v[224:227], v[240:243], v[112:127]
	ds_read_b128 v[200:203], v187 offset:64
	s_waitcnt lgkmcnt(4)
	v_mfma_f32_32x32x16_bf16 v[96:111], v[224:227], v[244:247], v[96:111]
	ds_read_b128 v[204:207], v187 offset:4672
	s_waitcnt lgkmcnt(4)
	v_mfma_f32_32x32x16_bf16 v[80:95], v[228:231], v[240:243], v[80:95]
	ds_read_b128 v[208:211], v187 offset:9280
	s_waitcnt lgkmcnt(5)
	v_mfma_f32_32x32x16_bf16 v[64:79], v[228:231], v[244:247], v[64:79]
	ds_read_b128 v[212:215], v176 offset:64
	s_waitcnt lgkmcnt(5)
	v_mfma_f32_32x32x16_bf16 v[48:63], v[232:235], v[240:243], v[48:63]
	ds_read_b128 v[216:219], v188 offset:36928
	s_waitcnt lgkmcnt(6)
	v_mfma_f32_32x32x16_bf16 v[32:47], v[232:235], v[244:247], v[32:47]
	ds_read_b128 v[220:223], v188 offset:41536
	s_waitcnt lgkmcnt(6)
	v_mfma_f32_32x32x16_bf16 v[16:31], v[236:239], v[240:243], v[16:31]
	s_waitcnt lgkmcnt(6)
	v_mfma_f32_32x32x16_bf16 v[0:15], v[236:239], v[244:247], v[0:15]
	s_waitcnt lgkmcnt(1)
	v_mfma_f32_32x32x16_bf16 v[112:127], v[200:203], v[216:219], v[112:127]
	ds_read_b128 v[224:227], v187 offset:96
	s_waitcnt lgkmcnt(1)
	v_mfma_f32_32x32x16_bf16 v[96:111], v[200:203], v[220:223], v[96:111]
	ds_read_b128 v[228:231], v187 offset:4704
	s_waitcnt lgkmcnt(3)
	v_mfma_f32_32x32x16_bf16 v[80:95], v[204:207], v[216:219], v[80:95]
	ds_read_b128 v[232:235], v187 offset:9312
	s_waitcnt lgkmcnt(3)
	v_mfma_f32_32x32x16_bf16 v[64:79], v[204:207], v[220:223], v[64:79]
	ds_read_b128 v[236:239], v176 offset:96
	s_waitcnt lgkmcnt(5)
	v_mfma_f32_32x32x16_bf16 v[48:63], v[208:211], v[216:219], v[48:63]
	ds_read_b128 v[240:243], v188 offset:36960
	s_waitcnt lgkmcnt(5)
	v_mfma_f32_32x32x16_bf16 v[32:47], v[208:211], v[220:223], v[32:47]
	ds_read_b128 v[244:247], v188 offset:41568
	s_waitcnt lgkmcnt(7)
	v_mfma_f32_32x32x16_bf16 v[16:31], v[212:215], v[216:219], v[16:31]
	s_waitcnt lgkmcnt(6)
	v_mfma_f32_32x32x16_bf16 v[0:15], v[212:215], v[220:223], v[0:15]
	s_waitcnt lgkmcnt(1)
	v_mfma_f32_32x32x16_bf16 v[112:127], v[224:227], v[240:243], v[112:127]
	s_waitcnt lgkmcnt(0)
	v_mfma_f32_32x32x16_bf16 v[96:111], v[224:227], v[244:247], v[96:111]
	s_waitcnt lgkmcnt(1)
	v_mfma_f32_32x32x16_bf16 v[80:95], v[228:231], v[240:243], v[80:95]
	s_waitcnt lgkmcnt(0)
	v_mfma_f32_32x32x16_bf16 v[64:79], v[228:231], v[244:247], v[64:79]
	s_waitcnt lgkmcnt(1)
	v_mfma_f32_32x32x16_bf16 v[48:63], v[232:235], v[240:243], v[48:63]
	s_waitcnt lgkmcnt(0)
	v_mfma_f32_32x32x16_bf16 v[32:47], v[232:235], v[244:247], v[32:47]
	s_waitcnt lgkmcnt(1)
	v_mfma_f32_32x32x16_bf16 v[16:31], v[236:239], v[240:243], v[16:31]
	s_waitcnt lgkmcnt(0)
	v_mfma_f32_32x32x16_bf16 v[0:15], v[236:239], v[244:247], v[0:15]
	s_mul_i32 s42, s6, 0x2000
	s_add_u32 s44, s30, s42
	s_addc_u32 s45, s31, 0
	s_lshl_b32 s42, s58, 1
	s_add_u32 s44, s44, s42
	s_addc_u32 s45, s45, 0
	s_add_u32 s44, s44, 0x7157900
	s_addc_u32 s45, s45, 0
	s_mov_b32 s43, 1
	v_max_f32_e32 v112, 0, v112
	v_max_f32_e32 v113, 0, v113
	v_mul_f32_e32 v112, v112, v112
	v_mul_f32_e32 v113, v113, v113
	v_cvt_pk_bf16_f32 v190, v112, v113
	v_max_f32_e32 v114, 0, v114
	v_max_f32_e32 v115, 0, v115
	v_mul_f32_e32 v114, v114, v114
	v_mul_f32_e32 v115, v115, v115
	v_cvt_pk_bf16_f32 v191, v114, v115
	v_max_f32_e32 v116, 0, v116
	v_max_f32_e32 v117, 0, v117
	v_mul_f32_e32 v116, v116, v116
	v_mul_f32_e32 v117, v117, v117
	v_cvt_pk_bf16_f32 v192, v116, v117
	v_max_f32_e32 v118, 0, v118
	v_max_f32_e32 v119, 0, v119
	v_mul_f32_e32 v118, v118, v118
	v_mul_f32_e32 v119, v119, v119
	v_cvt_pk_bf16_f32 v193, v118, v119
	v_max_f32_e32 v120, 0, v120
	v_max_f32_e32 v121, 0, v121
	v_mul_f32_e32 v120, v120, v120
	v_mul_f32_e32 v121, v121, v121
	v_cvt_pk_bf16_f32 v194, v120, v121
	v_max_f32_e32 v122, 0, v122
	v_max_f32_e32 v123, 0, v123
	v_mul_f32_e32 v122, v122, v122
	v_mul_f32_e32 v123, v123, v123
	v_cvt_pk_bf16_f32 v195, v122, v123
	v_max_f32_e32 v124, 0, v124
	v_max_f32_e32 v125, 0, v125
	v_mul_f32_e32 v124, v124, v124
	v_mul_f32_e32 v125, v125, v125
	v_cvt_pk_bf16_f32 v196, v124, v125
	v_max_f32_e32 v126, 0, v126
	v_max_f32_e32 v127, 0, v127
	v_mul_f32_e32 v126, v126, v126
	v_mul_f32_e32 v127, v127, v127
	v_cvt_pk_bf16_f32 v197, v126, v127
	v_max_f32_e32 v96, 0, v96
	v_max_f32_e32 v97, 0, v97
	v_mul_f32_e32 v96, v96, v96
	v_mul_f32_e32 v97, v97, v97
	v_cvt_pk_bf16_f32 v198, v96, v97
	v_max_f32_e32 v98, 0, v98
	v_max_f32_e32 v99, 0, v99
	v_mul_f32_e32 v98, v98, v98
	v_mul_f32_e32 v99, v99, v99
	v_cvt_pk_bf16_f32 v199, v98, v99
	v_max_f32_e32 v100, 0, v100
	v_max_f32_e32 v101, 0, v101
	v_mul_f32_e32 v100, v100, v100
	v_mul_f32_e32 v101, v101, v101
	v_cvt_pk_bf16_f32 v200, v100, v101
	v_max_f32_e32 v102, 0, v102
	v_max_f32_e32 v103, 0, v103
	v_mul_f32_e32 v102, v102, v102
	v_mul_f32_e32 v103, v103, v103
	v_cvt_pk_bf16_f32 v201, v102, v103
	v_max_f32_e32 v104, 0, v104
	v_max_f32_e32 v105, 0, v105
	v_mul_f32_e32 v104, v104, v104
	v_mul_f32_e32 v105, v105, v105
	v_cvt_pk_bf16_f32 v202, v104, v105
	v_max_f32_e32 v106, 0, v106
	v_max_f32_e32 v107, 0, v107
	v_mul_f32_e32 v106, v106, v106
	v_mul_f32_e32 v107, v107, v107
	v_cvt_pk_bf16_f32 v203, v106, v107
	v_max_f32_e32 v108, 0, v108
	v_max_f32_e32 v109, 0, v109
	v_mul_f32_e32 v108, v108, v108
	v_mul_f32_e32 v109, v109, v109
	v_cvt_pk_bf16_f32 v204, v108, v109
	v_max_f32_e32 v110, 0, v110
	v_max_f32_e32 v111, 0, v111
	v_mul_f32_e32 v110, v110, v110
	v_mul_f32_e32 v111, v111, v111
	v_cvt_pk_bf16_f32 v205, v110, v111
	v_max_f32_e32 v80, 0, v80
	v_max_f32_e32 v81, 0, v81
	v_mul_f32_e32 v80, v80, v80
	v_mul_f32_e32 v81, v81, v81
	v_cvt_pk_bf16_f32 v206, v80, v81
	v_max_f32_e32 v82, 0, v82
	v_max_f32_e32 v83, 0, v83
	v_mul_f32_e32 v82, v82, v82
	v_mul_f32_e32 v83, v83, v83
	v_cvt_pk_bf16_f32 v207, v82, v83
	v_max_f32_e32 v84, 0, v84
	v_max_f32_e32 v85, 0, v85
	v_mul_f32_e32 v84, v84, v84
	v_mul_f32_e32 v85, v85, v85
	v_cvt_pk_bf16_f32 v208, v84, v85
	v_max_f32_e32 v86, 0, v86
	v_max_f32_e32 v87, 0, v87
	v_mul_f32_e32 v86, v86, v86
	v_mul_f32_e32 v87, v87, v87
	v_cvt_pk_bf16_f32 v209, v86, v87
	v_max_f32_e32 v88, 0, v88
	v_max_f32_e32 v89, 0, v89
	v_mul_f32_e32 v88, v88, v88
	v_mul_f32_e32 v89, v89, v89
	v_cvt_pk_bf16_f32 v210, v88, v89
	v_max_f32_e32 v90, 0, v90
	v_max_f32_e32 v91, 0, v91
	v_mul_f32_e32 v90, v90, v90
	v_mul_f32_e32 v91, v91, v91
	v_cvt_pk_bf16_f32 v211, v90, v91
	v_max_f32_e32 v92, 0, v92
	v_max_f32_e32 v93, 0, v93
	v_mul_f32_e32 v92, v92, v92
	v_mul_f32_e32 v93, v93, v93
	v_cvt_pk_bf16_f32 v212, v92, v93
	v_max_f32_e32 v94, 0, v94
	v_max_f32_e32 v95, 0, v95
	v_mul_f32_e32 v94, v94, v94
	v_mul_f32_e32 v95, v95, v95
	v_cvt_pk_bf16_f32 v213, v94, v95
	v_max_f32_e32 v64, 0, v64
	v_max_f32_e32 v65, 0, v65
	v_mul_f32_e32 v64, v64, v64
	v_mul_f32_e32 v65, v65, v65
	v_cvt_pk_bf16_f32 v214, v64, v65
	v_max_f32_e32 v66, 0, v66
	v_max_f32_e32 v67, 0, v67
	v_mul_f32_e32 v66, v66, v66
	v_mul_f32_e32 v67, v67, v67
	v_cvt_pk_bf16_f32 v215, v66, v67
	v_max_f32_e32 v68, 0, v68
	v_max_f32_e32 v69, 0, v69
	v_mul_f32_e32 v68, v68, v68
	v_mul_f32_e32 v69, v69, v69
	v_cvt_pk_bf16_f32 v216, v68, v69
	v_max_f32_e32 v70, 0, v70
	v_max_f32_e32 v71, 0, v71
	v_mul_f32_e32 v70, v70, v70
	v_mul_f32_e32 v71, v71, v71
	v_cvt_pk_bf16_f32 v217, v70, v71
	v_max_f32_e32 v72, 0, v72
	v_max_f32_e32 v73, 0, v73
	v_mul_f32_e32 v72, v72, v72
	v_mul_f32_e32 v73, v73, v73
	v_cvt_pk_bf16_f32 v218, v72, v73
	v_max_f32_e32 v74, 0, v74
	v_max_f32_e32 v75, 0, v75
	v_mul_f32_e32 v74, v74, v74
	v_mul_f32_e32 v75, v75, v75
	v_cvt_pk_bf16_f32 v219, v74, v75
	v_max_f32_e32 v76, 0, v76
	v_max_f32_e32 v77, 0, v77
	v_mul_f32_e32 v76, v76, v76
	v_mul_f32_e32 v77, v77, v77
	v_cvt_pk_bf16_f32 v220, v76, v77
	v_max_f32_e32 v78, 0, v78
	v_max_f32_e32 v79, 0, v79
	v_mul_f32_e32 v78, v78, v78
	v_mul_f32_e32 v79, v79, v79
	v_cvt_pk_bf16_f32 v221, v78, v79
	v_max_f32_e32 v48, 0, v48
	v_max_f32_e32 v49, 0, v49
	v_mul_f32_e32 v48, v48, v48
	v_mul_f32_e32 v49, v49, v49
	v_cvt_pk_bf16_f32 v222, v48, v49
	v_max_f32_e32 v50, 0, v50
	v_max_f32_e32 v51, 0, v51
	v_mul_f32_e32 v50, v50, v50
	v_mul_f32_e32 v51, v51, v51
	v_cvt_pk_bf16_f32 v223, v50, v51
	v_max_f32_e32 v52, 0, v52
	v_max_f32_e32 v53, 0, v53
	v_mul_f32_e32 v52, v52, v52
	v_mul_f32_e32 v53, v53, v53
	v_cvt_pk_bf16_f32 v224, v52, v53
	v_max_f32_e32 v54, 0, v54
	v_max_f32_e32 v55, 0, v55
	v_mul_f32_e32 v54, v54, v54
	v_mul_f32_e32 v55, v55, v55
	v_cvt_pk_bf16_f32 v225, v54, v55
	v_max_f32_e32 v56, 0, v56
	v_max_f32_e32 v57, 0, v57
	v_mul_f32_e32 v56, v56, v56
	v_mul_f32_e32 v57, v57, v57
	v_cvt_pk_bf16_f32 v226, v56, v57
	v_max_f32_e32 v58, 0, v58
	v_max_f32_e32 v59, 0, v59
	v_mul_f32_e32 v58, v58, v58
	v_mul_f32_e32 v59, v59, v59
	v_cvt_pk_bf16_f32 v227, v58, v59
	v_max_f32_e32 v60, 0, v60
	v_max_f32_e32 v61, 0, v61
	v_mul_f32_e32 v60, v60, v60
	v_mul_f32_e32 v61, v61, v61
	v_cvt_pk_bf16_f32 v228, v60, v61
	v_max_f32_e32 v62, 0, v62
	v_max_f32_e32 v63, 0, v63
	v_mul_f32_e32 v62, v62, v62
	v_mul_f32_e32 v63, v63, v63
	v_cvt_pk_bf16_f32 v229, v62, v63
	v_max_f32_e32 v32, 0, v32
	v_max_f32_e32 v33, 0, v33
	v_mul_f32_e32 v32, v32, v32
	v_mul_f32_e32 v33, v33, v33
	v_cvt_pk_bf16_f32 v230, v32, v33
	v_max_f32_e32 v34, 0, v34
	v_max_f32_e32 v35, 0, v35
	v_mul_f32_e32 v34, v34, v34
	v_mul_f32_e32 v35, v35, v35
	v_cvt_pk_bf16_f32 v231, v34, v35
	v_max_f32_e32 v36, 0, v36
	v_max_f32_e32 v37, 0, v37
	v_mul_f32_e32 v36, v36, v36
	v_mul_f32_e32 v37, v37, v37
	v_cvt_pk_bf16_f32 v232, v36, v37
	v_max_f32_e32 v38, 0, v38
	v_max_f32_e32 v39, 0, v39
	v_mul_f32_e32 v38, v38, v38
	v_mul_f32_e32 v39, v39, v39
	v_cvt_pk_bf16_f32 v233, v38, v39
	v_max_f32_e32 v40, 0, v40
	v_max_f32_e32 v41, 0, v41
	v_mul_f32_e32 v40, v40, v40
	v_mul_f32_e32 v41, v41, v41
	v_cvt_pk_bf16_f32 v234, v40, v41
	v_max_f32_e32 v42, 0, v42
	v_max_f32_e32 v43, 0, v43
	v_mul_f32_e32 v42, v42, v42
	v_mul_f32_e32 v43, v43, v43
	v_cvt_pk_bf16_f32 v235, v42, v43
	v_max_f32_e32 v44, 0, v44
	v_max_f32_e32 v45, 0, v45
	v_mul_f32_e32 v44, v44, v44
	v_mul_f32_e32 v45, v45, v45
	v_cvt_pk_bf16_f32 v236, v44, v45
	v_max_f32_e32 v46, 0, v46
	v_max_f32_e32 v47, 0, v47
	v_mul_f32_e32 v46, v46, v46
	v_mul_f32_e32 v47, v47, v47
	v_cvt_pk_bf16_f32 v237, v46, v47
	v_max_f32_e32 v16, 0, v16
	v_max_f32_e32 v17, 0, v17
	v_mul_f32_e32 v16, v16, v16
	v_mul_f32_e32 v17, v17, v17
	v_cvt_pk_bf16_f32 v238, v16, v17
	v_max_f32_e32 v18, 0, v18
	v_max_f32_e32 v19, 0, v19
	v_mul_f32_e32 v18, v18, v18
	v_mul_f32_e32 v19, v19, v19
	v_cvt_pk_bf16_f32 v239, v18, v19
	v_max_f32_e32 v20, 0, v20
	v_max_f32_e32 v21, 0, v21
	v_mul_f32_e32 v20, v20, v20
	v_mul_f32_e32 v21, v21, v21
	v_cvt_pk_bf16_f32 v240, v20, v21
	v_max_f32_e32 v22, 0, v22
	v_max_f32_e32 v23, 0, v23
	v_mul_f32_e32 v22, v22, v22
	v_mul_f32_e32 v23, v23, v23
	v_cvt_pk_bf16_f32 v241, v22, v23
	v_max_f32_e32 v24, 0, v24
	v_max_f32_e32 v25, 0, v25
	v_mul_f32_e32 v24, v24, v24
	v_mul_f32_e32 v25, v25, v25
	v_cvt_pk_bf16_f32 v242, v24, v25
	v_max_f32_e32 v26, 0, v26
	v_max_f32_e32 v27, 0, v27
	v_mul_f32_e32 v26, v26, v26
	v_mul_f32_e32 v27, v27, v27
	v_cvt_pk_bf16_f32 v243, v26, v27
	v_max_f32_e32 v28, 0, v28
	v_max_f32_e32 v29, 0, v29
	v_mul_f32_e32 v28, v28, v28
	v_mul_f32_e32 v29, v29, v29
	v_cvt_pk_bf16_f32 v244, v28, v29
	v_max_f32_e32 v30, 0, v30
	v_max_f32_e32 v31, 0, v31
	v_mul_f32_e32 v30, v30, v30
	v_mul_f32_e32 v31, v31, v31
	v_cvt_pk_bf16_f32 v245, v30, v31
	v_max_f32_e32 v0, 0, v0
	v_max_f32_e32 v1, 0, v1
	v_mul_f32_e32 v0, v0, v0
	v_mul_f32_e32 v1, v1, v1
	v_cvt_pk_bf16_f32 v246, v0, v1
	v_max_f32_e32 v2, 0, v2
	v_max_f32_e32 v3, 0, v3
	v_mul_f32_e32 v2, v2, v2
	v_mul_f32_e32 v3, v3, v3
	v_cvt_pk_bf16_f32 v247, v2, v3
	v_max_f32_e32 v4, 0, v4
	v_max_f32_e32 v5, 0, v5
	v_mul_f32_e32 v4, v4, v4
	v_mul_f32_e32 v5, v5, v5
	v_cvt_pk_bf16_f32 v248, v4, v5
	v_max_f32_e32 v6, 0, v6
	v_max_f32_e32 v7, 0, v7
	v_mul_f32_e32 v6, v6, v6
	v_mul_f32_e32 v7, v7, v7
	v_cvt_pk_bf16_f32 v249, v6, v7
	v_max_f32_e32 v8, 0, v8
	v_max_f32_e32 v9, 0, v9
	v_mul_f32_e32 v8, v8, v8
	v_mul_f32_e32 v9, v9, v9
	v_cvt_pk_bf16_f32 v250, v8, v9
	v_max_f32_e32 v10, 0, v10
	v_max_f32_e32 v11, 0, v11
	v_mul_f32_e32 v10, v10, v10
	v_mul_f32_e32 v11, v11, v11
	v_cvt_pk_bf16_f32 v251, v10, v11
	v_max_f32_e32 v12, 0, v12
	v_max_f32_e32 v13, 0, v13
	v_mul_f32_e32 v12, v12, v12
	v_mul_f32_e32 v13, v13, v13
	v_cvt_pk_bf16_f32 v252, v12, v13
	v_max_f32_e32 v14, 0, v14
	v_max_f32_e32 v15, 0, v15
	v_mul_f32_e32 v14, v14, v14
	v_mul_f32_e32 v15, v15, v15
	v_cvt_pk_bf16_f32 v253, v14, v15
	s_add_i32 s57, s57, s22
	s_add_i32 s56, s56, s22
	s_cmpk_lt_u32 s57, 0x240
	s_cbranch_scc1 .LBB0_996
	v_and_b32_e32 v3, 15, v182
	v_lshrrev_b32_e32 v4, 4, v182
	v_mul_u32_u24_e32 v2, 0x2000, v4
	v_lshl_add_u32 v2, v3, 4, v2
	v_mul_u32_u24_e32 v1, 0x110, v4
	v_lshl_add_u32 v1, v3, 4, v1
	v_lshrrev_b32_e32 v3, 7, v182
	v_bfe_u32 v4, v182, 5, 1
	v_lshlrev_b32_e32 v3, 6, v3
	v_lshl_or_b32 v3, v4, 2, v3
	v_mul_u32_u24_e32 v3, 136, v3
	v_and_b32_e32 v4, 0x5f, v182
	v_add_lshl_u32 v0, v3, v4, 1
	s_barrier
	ds_write_b16 v0, v190
	ds_write_b16_d16_hi v0, v190 offset:272
	ds_write_b16 v0, v191 offset:544
	ds_write_b16_d16_hi v0, v191 offset:816
	ds_write_b16 v0, v192 offset:2176
	ds_write_b16_d16_hi v0, v192 offset:2448
	ds_write_b16 v0, v193 offset:2720
	ds_write_b16_d16_hi v0, v193 offset:2992
	ds_write_b16 v0, v194 offset:4352
	ds_write_b16_d16_hi v0, v194 offset:4624
	ds_write_b16 v0, v195 offset:4896
	ds_write_b16_d16_hi v0, v195 offset:5168
	ds_write_b16 v0, v196 offset:6528
	ds_write_b16_d16_hi v0, v196 offset:6800
	ds_write_b16 v0, v197 offset:7072
	ds_write_b16_d16_hi v0, v197 offset:7344
	ds_write_b16 v0, v198 offset:64
	ds_write_b16_d16_hi v0, v198 offset:336
	ds_write_b16 v0, v199 offset:608
	ds_write_b16_d16_hi v0, v199 offset:880
	ds_write_b16 v0, v200 offset:2240
	ds_write_b16_d16_hi v0, v200 offset:2512
	ds_write_b16 v0, v201 offset:2784
	ds_write_b16_d16_hi v0, v201 offset:3056
	ds_write_b16 v0, v202 offset:4416
	ds_write_b16_d16_hi v0, v202 offset:4688
	ds_write_b16 v0, v203 offset:4960
	ds_write_b16_d16_hi v0, v203 offset:5232
	ds_write_b16 v0, v204 offset:6592
	ds_write_b16_d16_hi v0, v204 offset:6864
	ds_write_b16 v0, v205 offset:7136
	ds_write_b16_d16_hi v0, v205 offset:7408
	ds_write_b16 v0, v206 offset:8704
	ds_write_b16_d16_hi v0, v206 offset:8976
	ds_write_b16 v0, v207 offset:9248
	ds_write_b16_d16_hi v0, v207 offset:9520
	ds_write_b16 v0, v208 offset:10880
	ds_write_b16_d16_hi v0, v208 offset:11152
	ds_write_b16 v0, v209 offset:11424
	ds_write_b16_d16_hi v0, v209 offset:11696
	ds_write_b16 v0, v210 offset:13056
	ds_write_b16_d16_hi v0, v210 offset:13328
	ds_write_b16 v0, v211 offset:13600
	ds_write_b16_d16_hi v0, v211 offset:13872
	ds_write_b16 v0, v212 offset:15232
	ds_write_b16_d16_hi v0, v212 offset:15504
	ds_write_b16 v0, v213 offset:15776
	ds_write_b16_d16_hi v0, v213 offset:16048
	ds_write_b16 v0, v214 offset:8768
	ds_write_b16_d16_hi v0, v214 offset:9040
	ds_write_b16 v0, v215 offset:9312
	ds_write_b16_d16_hi v0, v215 offset:9584
	ds_write_b16 v0, v216 offset:10944
	ds_write_b16_d16_hi v0, v216 offset:11216
	ds_write_b16 v0, v217 offset:11488
	ds_write_b16_d16_hi v0, v217 offset:11760
	ds_write_b16 v0, v218 offset:13120
	ds_write_b16_d16_hi v0, v218 offset:13392
	ds_write_b16 v0, v219 offset:13664
	ds_write_b16_d16_hi v0, v219 offset:13936
	ds_write_b16 v0, v220 offset:15296
	ds_write_b16_d16_hi v0, v220 offset:15568
	ds_write_b16 v0, v221 offset:15840
	ds_write_b16_d16_hi v0, v221 offset:16112
	s_waitcnt lgkmcnt(0)
	s_barrier
	ds_read_b128 v[8:11], v1
	ds_read_b128 v[12:15], v1 offset:4352
	ds_read_b128 v[16:19], v1 offset:8704
	ds_read_b128 v[20:23], v1 offset:13056
	ds_read_b128 v[24:27], v1 offset:17408
	ds_read_b128 v[28:31], v1 offset:21760
	ds_read_b128 v[32:35], v1 offset:26112
	ds_read_b128 v[36:39], v1 offset:30464
	s_add_u32 s38, s44, 0x0
	s_addc_u32 s39, s45, 0
	s_waitcnt lgkmcnt(7)
	global_store_dwordx4 v2, v[8:11], s[38:39]
	s_add_u32 s38, s44, 0x20000
	s_addc_u32 s39, s45, 0
	s_waitcnt lgkmcnt(6)
	global_store_dwordx4 v2, v[12:15], s[38:39]
	s_add_u32 s38, s44, 0x40000
	s_addc_u32 s39, s45, 0
	s_waitcnt lgkmcnt(5)
	global_store_dwordx4 v2, v[16:19], s[38:39]
	s_add_u32 s38, s44, 0x60000
	s_addc_u32 s39, s45, 0
	s_waitcnt lgkmcnt(4)
	global_store_dwordx4 v2, v[20:23], s[38:39]
	s_add_u32 s38, s44, 0x100000
	s_addc_u32 s39, s45, 0
	s_waitcnt lgkmcnt(3)
	global_store_dwordx4 v2, v[24:27], s[38:39]
	s_add_u32 s38, s44, 0x120000
	s_addc_u32 s39, s45, 0
	s_waitcnt lgkmcnt(2)
	global_store_dwordx4 v2, v[28:31], s[38:39]
	s_add_u32 s38, s44, 0x140000
	s_addc_u32 s39, s45, 0
	s_waitcnt lgkmcnt(1)
	global_store_dwordx4 v2, v[32:35], s[38:39]
	s_add_u32 s38, s44, 0x160000
	s_addc_u32 s39, s45, 0
	s_waitcnt lgkmcnt(0)
	global_store_dwordx4 v2, v[36:39], s[38:39]
	s_barrier
	ds_write_b16 v0, v222
	ds_write_b16_d16_hi v0, v222 offset:272
	ds_write_b16 v0, v223 offset:544
	ds_write_b16_d16_hi v0, v223 offset:816
	ds_write_b16 v0, v224 offset:2176
	ds_write_b16_d16_hi v0, v224 offset:2448
	ds_write_b16 v0, v225 offset:2720
	ds_write_b16_d16_hi v0, v225 offset:2992
	ds_write_b16 v0, v226 offset:4352
	ds_write_b16_d16_hi v0, v226 offset:4624
	ds_write_b16 v0, v227 offset:4896
	ds_write_b16_d16_hi v0, v227 offset:5168
	ds_write_b16 v0, v228 offset:6528
	ds_write_b16_d16_hi v0, v228 offset:6800
	ds_write_b16 v0, v229 offset:7072
	ds_write_b16_d16_hi v0, v229 offset:7344
	ds_write_b16 v0, v230 offset:64
	ds_write_b16_d16_hi v0, v230 offset:336
	ds_write_b16 v0, v231 offset:608
	ds_write_b16_d16_hi v0, v231 offset:880
	ds_write_b16 v0, v232 offset:2240
	ds_write_b16_d16_hi v0, v232 offset:2512
	ds_write_b16 v0, v233 offset:2784
	ds_write_b16_d16_hi v0, v233 offset:3056
	ds_write_b16 v0, v234 offset:4416
	ds_write_b16_d16_hi v0, v234 offset:4688
	ds_write_b16 v0, v235 offset:4960
	ds_write_b16_d16_hi v0, v235 offset:5232
	ds_write_b16 v0, v236 offset:6592
	ds_write_b16_d16_hi v0, v236 offset:6864
	ds_write_b16 v0, v237 offset:7136
	ds_write_b16_d16_hi v0, v237 offset:7408
	ds_write_b16 v0, v238 offset:8704
	ds_write_b16_d16_hi v0, v238 offset:8976
	ds_write_b16 v0, v239 offset:9248
	ds_write_b16_d16_hi v0, v239 offset:9520
	ds_write_b16 v0, v240 offset:10880
	ds_write_b16_d16_hi v0, v240 offset:11152
	ds_write_b16 v0, v241 offset:11424
	ds_write_b16_d16_hi v0, v241 offset:11696
	ds_write_b16 v0, v242 offset:13056
	ds_write_b16_d16_hi v0, v242 offset:13328
	ds_write_b16 v0, v243 offset:13600
	ds_write_b16_d16_hi v0, v243 offset:13872
	ds_write_b16 v0, v244 offset:15232
	ds_write_b16_d16_hi v0, v244 offset:15504
	ds_write_b16 v0, v245 offset:15776
	ds_write_b16_d16_hi v0, v245 offset:16048
	ds_write_b16 v0, v246 offset:8768
	ds_write_b16_d16_hi v0, v246 offset:9040
	ds_write_b16 v0, v247 offset:9312
	ds_write_b16_d16_hi v0, v247 offset:9584
	ds_write_b16 v0, v248 offset:10944
	ds_write_b16_d16_hi v0, v248 offset:11216
	ds_write_b16 v0, v249 offset:11488
	ds_write_b16_d16_hi v0, v249 offset:11760
	ds_write_b16 v0, v250 offset:13120
	ds_write_b16_d16_hi v0, v250 offset:13392
	ds_write_b16 v0, v251 offset:13664
	ds_write_b16_d16_hi v0, v251 offset:13936
	ds_write_b16 v0, v252 offset:15296
	ds_write_b16_d16_hi v0, v252 offset:15568
	ds_write_b16 v0, v253 offset:15840
	ds_write_b16_d16_hi v0, v253 offset:16112
	s_waitcnt lgkmcnt(0)
	s_barrier
	ds_read_b128 v[8:11], v1
	ds_read_b128 v[12:15], v1 offset:4352
	ds_read_b128 v[16:19], v1 offset:8704
	ds_read_b128 v[20:23], v1 offset:13056
	ds_read_b128 v[24:27], v1 offset:17408
	ds_read_b128 v[28:31], v1 offset:21760
	ds_read_b128 v[32:35], v1 offset:26112
	ds_read_b128 v[36:39], v1 offset:30464
	s_add_u32 s38, s44, 0x80000
	s_addc_u32 s39, s45, 0
	s_waitcnt lgkmcnt(7)
	global_store_dwordx4 v2, v[8:11], s[38:39]
	s_add_u32 s38, s44, 0xa0000
	s_addc_u32 s39, s45, 0
	s_waitcnt lgkmcnt(6)
	global_store_dwordx4 v2, v[12:15], s[38:39]
	s_add_u32 s38, s44, 0xc0000
	s_addc_u32 s39, s45, 0
	s_waitcnt lgkmcnt(5)
	global_store_dwordx4 v2, v[16:19], s[38:39]
	s_add_u32 s38, s44, 0xe0000
	s_addc_u32 s39, s45, 0
	s_waitcnt lgkmcnt(4)
	global_store_dwordx4 v2, v[20:23], s[38:39]
	s_add_u32 s38, s44, 0x180000
	s_addc_u32 s39, s45, 0
	s_waitcnt lgkmcnt(3)
	global_store_dwordx4 v2, v[24:27], s[38:39]
	s_add_u32 s38, s44, 0x1a0000
	s_addc_u32 s39, s45, 0
	s_waitcnt lgkmcnt(2)
	global_store_dwordx4 v2, v[28:31], s[38:39]
	s_add_u32 s38, s44, 0x1c0000
	s_addc_u32 s39, s45, 0
	s_waitcnt lgkmcnt(1)
	global_store_dwordx4 v2, v[32:35], s[38:39]
	s_add_u32 s38, s44, 0x1e0000
	s_addc_u32 s39, s45, 0
	s_waitcnt lgkmcnt(0)
	global_store_dwordx4 v2, v[36:39], s[38:39]
	s_mov_b32 s43, 0
	s_branch .LBB0_989

.LBB0_1284:
	ds_read_b128 v[216:219], v176 offset:36864
	ds_read_b128 v[200:203], v188
	ds_read_b128 v[220:223], v176 offset:41472
	ds_read_b128 v[204:207], v188 offset:4608
	ds_read_b128 v[208:211], v188 offset:9216
	ds_read_b128 v[212:215], v187
	s_waitcnt lgkmcnt(4)
	v_mfma_f32_32x32x16_bf16 v[112:127], v[200:203], v[216:219], v[112:127]
	ds_read_b128 v[240:243], v176 offset:36896
	global_load_dwordx4 v[140:143], v190, s[44:45]
	s_waitcnt lgkmcnt(4)
	v_mfma_f32_32x32x16_bf16 v[96:111], v[200:203], v[220:223], v[96:111]
	ds_read_b128 v[224:227], v188 offset:32
	global_load_dwordx4 v[164:167], v190, s[42:43]
	s_waitcnt lgkmcnt(4)
	v_mfma_f32_32x32x16_bf16 v[80:95], v[204:207], v[216:219], v[80:95]
	ds_read_b128 v[244:247], v176 offset:41504
	global_load_dwordx4 v[128:131], v191, s[42:43]
	s_waitcnt lgkmcnt(5)
	v_mfma_f32_32x32x16_bf16 v[64:79], v[204:207], v[220:223], v[64:79]
	ds_read_b128 v[228:231], v188 offset:4640
	global_load_dwordx4 v[132:135], v192, s[42:43]
	s_waitcnt lgkmcnt(5)
	v_mfma_f32_32x32x16_bf16 v[48:63], v[208:211], v[216:219], v[48:63]
	ds_read_b128 v[232:235], v188 offset:9248
	global_load_dwordx4 v[136:139], v193, s[42:43]
	s_waitcnt lgkmcnt(6)
	v_mfma_f32_32x32x16_bf16 v[32:47], v[208:211], v[220:223], v[32:47]
	ds_read_b128 v[236:239], v187 offset:32
	global_load_dwordx4 v[144:147], v194, s[42:43]
	s_waitcnt lgkmcnt(6)
	v_mfma_f32_32x32x16_bf16 v[16:31], v[212:215], v[216:219], v[16:31]
	global_load_dwordx4 v[148:151], v195, s[42:43]
	s_waitcnt lgkmcnt(6)
	v_mfma_f32_32x32x16_bf16 v[0:15], v[212:215], v[220:223], v[0:15]
	global_load_dwordx4 v[152:155], v196, s[42:43]
	s_waitcnt lgkmcnt(4)
	v_mfma_f32_32x32x16_bf16 v[112:127], v[224:227], v[240:243], v[112:127]
	ds_read_b128 v[200:203], v188 offset:64
	global_load_dwordx4 v[156:159], v197, s[42:43]
	s_waitcnt lgkmcnt(4)
	v_mfma_f32_32x32x16_bf16 v[96:111], v[224:227], v[244:247], v[96:111]
	ds_read_b128 v[204:207], v188 offset:4672
	global_load_dwordx4 v[160:163], v191, s[44:45]
	s_waitcnt lgkmcnt(4)
	v_mfma_f32_32x32x16_bf16 v[80:95], v[228:231], v[240:243], v[80:95]
	ds_read_b128 v[208:211], v188 offset:9280
	global_load_dwordx4 v[168:171], v192, s[44:45]
	s_waitcnt lgkmcnt(5)
	v_mfma_f32_32x32x16_bf16 v[64:79], v[228:231], v[244:247], v[64:79]
	ds_read_b128 v[212:215], v187 offset:64
	global_load_dwordx4 v[172:175], v193, s[44:45]
	s_add_u32 s42, s42, 0x80
	s_addc_u32 s43, s43, 0
	s_add_u32 s44, s44, 0x80
	s_addc_u32 s45, s45, 0
	s_add_u32 s16, s16, 0x80
	s_waitcnt lgkmcnt(5)
	v_mfma_f32_32x32x16_bf16 v[48:63], v[232:235], v[240:243], v[48:63]
	ds_read_b128 v[216:219], v176 offset:36928
	s_waitcnt lgkmcnt(6)
	v_mfma_f32_32x32x16_bf16 v[32:47], v[232:235], v[244:247], v[32:47]
	ds_read_b128 v[220:223], v176 offset:41536
	s_waitcnt lgkmcnt(6)
	v_mfma_f32_32x32x16_bf16 v[16:31], v[236:239], v[240:243], v[16:31]
	s_waitcnt lgkmcnt(6)
	v_mfma_f32_32x32x16_bf16 v[0:15], v[236:239], v[244:247], v[0:15]
	s_waitcnt lgkmcnt(1)
	v_mfma_f32_32x32x16_bf16 v[112:127], v[200:203], v[216:219], v[112:127]
	ds_read_b128 v[224:227], v188 offset:96
	s_waitcnt lgkmcnt(1)
	v_mfma_f32_32x32x16_bf16 v[96:111], v[200:203], v[220:223], v[96:111]
	ds_read_b128 v[228:231], v188 offset:4704
	s_waitcnt lgkmcnt(3)
	v_mfma_f32_32x32x16_bf16 v[80:95], v[204:207], v[216:219], v[80:95]
	ds_read_b128 v[232:235], v188 offset:9312
	s_waitcnt lgkmcnt(3)
	v_mfma_f32_32x32x16_bf16 v[64:79], v[204:207], v[220:223], v[64:79]
	ds_read_b128 v[236:239], v187 offset:96
	s_waitcnt lgkmcnt(5)
	v_mfma_f32_32x32x16_bf16 v[48:63], v[208:211], v[216:219], v[48:63]
	ds_read_b128 v[240:243], v176 offset:36960
	s_waitcnt lgkmcnt(5)
	v_mfma_f32_32x32x16_bf16 v[32:47], v[208:211], v[220:223], v[32:47]
	ds_read_b128 v[244:247], v176 offset:41568
	s_waitcnt lgkmcnt(7)
	v_mfma_f32_32x32x16_bf16 v[16:31], v[212:215], v[216:219], v[16:31]
	s_waitcnt lgkmcnt(6)
	v_mfma_f32_32x32x16_bf16 v[0:15], v[212:215], v[220:223], v[0:15]
	s_waitcnt lgkmcnt(0)
	s_barrier
	s_waitcnt vmcnt(0)
	s_waitcnt lgkmcnt(1)
	v_mfma_f32_32x32x16_bf16 v[112:127], v[224:227], v[240:243], v[112:127]
	ds_write_b128 v189, v[164:167]
	ds_write_b128 v189, v[128:131] offset:4608
	s_waitcnt lgkmcnt(2)
	v_mfma_f32_32x32x16_bf16 v[96:111], v[224:227], v[244:247], v[96:111]
	ds_write_b128 v189, v[132:135] offset:9216
	s_waitcnt lgkmcnt(4)
	v_mfma_f32_32x32x16_bf16 v[80:95], v[228:231], v[240:243], v[80:95]
	ds_write_b128 v189, v[136:139] offset:13824
	ds_write_b128 v189, v[144:147] offset:18432
	s_waitcnt lgkmcnt(5)
	v_mfma_f32_32x32x16_bf16 v[64:79], v[228:231], v[244:247], v[64:79]
	ds_write_b128 v189, v[148:151] offset:23040
	s_waitcnt lgkmcnt(7)
	v_mfma_f32_32x32x16_bf16 v[48:63], v[232:235], v[240:243], v[48:63]
	ds_write_b128 v189, v[152:155] offset:27648
	ds_write_b128 v189, v[156:159] offset:32256
	s_waitcnt lgkmcnt(8)
	v_mfma_f32_32x32x16_bf16 v[32:47], v[232:235], v[244:247], v[32:47]
	ds_write_b128 v189, v[140:143] offset:36864
	s_waitcnt lgkmcnt(10)
	v_mfma_f32_32x32x16_bf16 v[16:31], v[236:239], v[240:243], v[16:31]
	ds_write_b128 v189, v[160:163] offset:41472
	ds_write_b128 v189, v[168:171] offset:46080
	s_waitcnt lgkmcnt(11)
	v_mfma_f32_32x32x16_bf16 v[0:15], v[236:239], v[244:247], v[0:15]
	ds_write_b128 v189, v[172:175] offset:50688
	s_waitcnt lgkmcnt(0)
	s_barrier
	s_cmpk_lg_i32 s16, 0x780
	s_cbranch_scc1 .LBB0_1284
	ds_read_b128 v[216:219], v176 offset:36864
	ds_read_b128 v[200:203], v188
	ds_read_b128 v[220:223], v176 offset:41472
	ds_read_b128 v[204:207], v188 offset:4608
	ds_read_b128 v[208:211], v188 offset:9216
	ds_read_b128 v[212:215], v187
	s_waitcnt lgkmcnt(4)
	v_mfma_f32_32x32x16_bf16 v[112:127], v[200:203], v[216:219], v[112:127]
	ds_read_b128 v[240:243], v176 offset:36896
	s_waitcnt lgkmcnt(4)
	v_mfma_f32_32x32x16_bf16 v[96:111], v[200:203], v[220:223], v[96:111]
	ds_read_b128 v[224:227], v188 offset:32
	s_waitcnt lgkmcnt(4)
	v_mfma_f32_32x32x16_bf16 v[80:95], v[204:207], v[216:219], v[80:95]
	ds_read_b128 v[244:247], v176 offset:41504
	s_waitcnt lgkmcnt(5)
	v_mfma_f32_32x32x16_bf16 v[64:79], v[204:207], v[220:223], v[64:79]
	ds_read_b128 v[228:231], v188 offset:4640
	s_waitcnt lgkmcnt(5)
	v_mfma_f32_32x32x16_bf16 v[48:63], v[208:211], v[216:219], v[48:63]
	ds_read_b128 v[232:235], v188 offset:9248
	s_waitcnt lgkmcnt(6)
	v_mfma_f32_32x32x16_bf16 v[32:47], v[208:211], v[220:223], v[32:47]
	ds_read_b128 v[236:239], v187 offset:32
	s_waitcnt lgkmcnt(6)
	v_mfma_f32_32x32x16_bf16 v[16:31], v[212:215], v[216:219], v[16:31]
	s_waitcnt lgkmcnt(6)
	v_mfma_f32_32x32x16_bf16 v[0:15], v[212:215], v[220:223], v[0:15]
	s_waitcnt lgkmcnt(4)
	v_mfma_f32_32x32x16_bf16 v[112:127], v[224:227], v[240:243], v[112:127]
	ds_read_b128 v[200:203], v188 offset:64
	s_waitcnt lgkmcnt(4)
	v_mfma_f32_32x32x16_bf16 v[96:111], v[224:227], v[244:247], v[96:111]
	ds_read_b128 v[204:207], v188 offset:4672
	s_waitcnt lgkmcnt(4)
	v_mfma_f32_32x32x16_bf16 v[80:95], v[228:231], v[240:243], v[80:95]
	ds_read_b128 v[208:211], v188 offset:9280
	s_waitcnt lgkmcnt(5)
	v_mfma_f32_32x32x16_bf16 v[64:79], v[228:231], v[244:247], v[64:79]
	ds_read_b128 v[212:215], v187 offset:64
	s_waitcnt lgkmcnt(5)
	v_mfma_f32_32x32x16_bf16 v[48:63], v[232:235], v[240:243], v[48:63]
	ds_read_b128 v[216:219], v176 offset:36928
	s_waitcnt lgkmcnt(6)
	v_mfma_f32_32x32x16_bf16 v[32:47], v[232:235], v[244:247], v[32:47]
	ds_read_b128 v[220:223], v176 offset:41536
	s_waitcnt lgkmcnt(6)
	v_mfma_f32_32x32x16_bf16 v[16:31], v[236:239], v[240:243], v[16:31]
	s_waitcnt lgkmcnt(6)
	v_mfma_f32_32x32x16_bf16 v[0:15], v[236:239], v[244:247], v[0:15]
	s_waitcnt lgkmcnt(1)
	v_mfma_f32_32x32x16_bf16 v[112:127], v[200:203], v[216:219], v[112:127]
	ds_read_b128 v[224:227], v188 offset:96
	s_waitcnt lgkmcnt(1)
	v_mfma_f32_32x32x16_bf16 v[96:111], v[200:203], v[220:223], v[96:111]
	ds_read_b128 v[228:231], v188 offset:4704
	s_waitcnt lgkmcnt(3)
	v_mfma_f32_32x32x16_bf16 v[80:95], v[204:207], v[216:219], v[80:95]
	ds_read_b128 v[232:235], v188 offset:9312
	s_waitcnt lgkmcnt(3)
	v_mfma_f32_32x32x16_bf16 v[64:79], v[204:207], v[220:223], v[64:79]
	ds_read_b128 v[236:239], v187 offset:96
	s_waitcnt lgkmcnt(5)
	v_mfma_f32_32x32x16_bf16 v[48:63], v[208:211], v[216:219], v[48:63]
	ds_read_b128 v[240:243], v176 offset:36960
	s_waitcnt lgkmcnt(5)
	v_mfma_f32_32x32x16_bf16 v[32:47], v[208:211], v[220:223], v[32:47]
	ds_read_b128 v[244:247], v176 offset:41568
	s_waitcnt lgkmcnt(7)
	v_mfma_f32_32x32x16_bf16 v[16:31], v[212:215], v[216:219], v[16:31]
	s_waitcnt lgkmcnt(6)
	v_mfma_f32_32x32x16_bf16 v[0:15], v[212:215], v[220:223], v[0:15]
	s_waitcnt lgkmcnt(1)
	v_mfma_f32_32x32x16_bf16 v[112:127], v[224:227], v[240:243], v[112:127]
	s_waitcnt lgkmcnt(0)
	v_mfma_f32_32x32x16_bf16 v[96:111], v[224:227], v[244:247], v[96:111]
	s_waitcnt lgkmcnt(1)
	v_mfma_f32_32x32x16_bf16 v[80:95], v[228:231], v[240:243], v[80:95]
	s_waitcnt lgkmcnt(0)
	v_mfma_f32_32x32x16_bf16 v[64:79], v[228:231], v[244:247], v[64:79]
	s_waitcnt lgkmcnt(1)
	v_mfma_f32_32x32x16_bf16 v[48:63], v[232:235], v[240:243], v[48:63]
	s_waitcnt lgkmcnt(0)
	v_mfma_f32_32x32x16_bf16 v[32:47], v[232:235], v[244:247], v[32:47]
	s_waitcnt lgkmcnt(1)
	v_mfma_f32_32x32x16_bf16 v[16:31], v[236:239], v[240:243], v[16:31]
	s_waitcnt lgkmcnt(0)
	v_mfma_f32_32x32x16_bf16 v[0:15], v[236:239], v[244:247], v[0:15]
	s_mul_i32 s41, s12, 0x1240
	s_add_u32 s42, s30, s41
	s_addc_u32 s43, s31, 0
	s_lshl_b32 s41, s8, 1
	s_add_u32 s42, s42, s41
	s_addc_u32 s43, s43, 0
	s_add_u32 s42, s42, 0x7157900
	s_addc_u32 s43, s43, 0
	v_and_b32_e32 v131, 15, v182
	v_lshrrev_b32_e32 v172, 4, v182
	v_lshl_add_u32 v130, v131, 3, s8
	s_movk_i32 s41, 0x920
	v_cmp_gt_u32_e64 s[44:45], s41, v130
	v_mul_u32_u24_e32 v164, 0x1240, v172
	v_lshl_add_u32 v164, v131, 4, v164
	v_add_u32_e32 v165, 0x12400, v164
	v_add_u32_e32 v166, 0x24800, v164
	v_add_u32_e32 v167, 0x36c00, v164
	v_add_u32_e32 v168, 0x92000, v164
	v_add_u32_e32 v169, 0xa4400, v164
	v_add_u32_e32 v170, 0xb6800, v164
	v_add_u32_e32 v171, 0xc8c00, v164
	v_mul_u32_u24_e32 v129, 0x110, v172
	v_lshl_add_u32 v129, v131, 4, v129
	v_lshrrev_b32_e32 v131, 7, v182
	v_bfe_u32 v172, v182, 5, 1
	v_lshlrev_b32_e32 v131, 6, v131
	v_lshl_or_b32 v131, v172, 2, v131
	v_mul_u32_u24_e32 v131, 136, v131
	v_and_b32_e32 v172, 0x5f, v182
	v_add_lshl_u32 v128, v131, v172, 1
	s_barrier
	v_cvt_pk_bf16_f32 v112, v112, v113
	v_cvt_pk_bf16_f32 v114, v114, v115
	v_cvt_pk_bf16_f32 v116, v116, v117
	v_cvt_pk_bf16_f32 v118, v118, v119
	v_cvt_pk_bf16_f32 v120, v120, v121
	v_cvt_pk_bf16_f32 v122, v122, v123
	v_cvt_pk_bf16_f32 v124, v124, v125
	v_cvt_pk_bf16_f32 v126, v126, v127
	v_cvt_pk_bf16_f32 v96, v96, v97
	v_cvt_pk_bf16_f32 v98, v98, v99
	v_cvt_pk_bf16_f32 v100, v100, v101
	v_cvt_pk_bf16_f32 v102, v102, v103
	v_cvt_pk_bf16_f32 v104, v104, v105
	v_cvt_pk_bf16_f32 v106, v106, v107
	v_cvt_pk_bf16_f32 v108, v108, v109
	v_cvt_pk_bf16_f32 v110, v110, v111
	v_cvt_pk_bf16_f32 v80, v80, v81
	v_cvt_pk_bf16_f32 v82, v82, v83
	v_cvt_pk_bf16_f32 v84, v84, v85
	v_cvt_pk_bf16_f32 v86, v86, v87
	v_cvt_pk_bf16_f32 v88, v88, v89
	v_cvt_pk_bf16_f32 v90, v90, v91
	v_cvt_pk_bf16_f32 v92, v92, v93
	v_cvt_pk_bf16_f32 v94, v94, v95
	v_cvt_pk_bf16_f32 v64, v64, v65
	v_cvt_pk_bf16_f32 v66, v66, v67
	v_cvt_pk_bf16_f32 v68, v68, v69
	v_cvt_pk_bf16_f32 v70, v70, v71
	v_cvt_pk_bf16_f32 v72, v72, v73
	v_cvt_pk_bf16_f32 v74, v74, v75
	v_cvt_pk_bf16_f32 v76, v76, v77
	v_cvt_pk_bf16_f32 v78, v78, v79
	ds_write_b16 v128, v112
	ds_write_b16_d16_hi v128, v112 offset:272
	ds_write_b16 v128, v114 offset:544
	ds_write_b16_d16_hi v128, v114 offset:816
	ds_write_b16 v128, v116 offset:2176
	ds_write_b16_d16_hi v128, v116 offset:2448
	ds_write_b16 v128, v118 offset:2720
	ds_write_b16_d16_hi v128, v118 offset:2992
	ds_write_b16 v128, v120 offset:4352
	ds_write_b16_d16_hi v128, v120 offset:4624
	ds_write_b16 v128, v122 offset:4896
	ds_write_b16_d16_hi v128, v122 offset:5168
	ds_write_b16 v128, v124 offset:6528
	ds_write_b16_d16_hi v128, v124 offset:6800
	ds_write_b16 v128, v126 offset:7072
	ds_write_b16_d16_hi v128, v126 offset:7344
	ds_write_b16 v128, v96 offset:64
	ds_write_b16_d16_hi v128, v96 offset:336
	ds_write_b16 v128, v98 offset:608
	ds_write_b16_d16_hi v128, v98 offset:880
	ds_write_b16 v128, v100 offset:2240
	ds_write_b16_d16_hi v128, v100 offset:2512
	ds_write_b16 v128, v102 offset:2784
	ds_write_b16_d16_hi v128, v102 offset:3056
	ds_write_b16 v128, v104 offset:4416
	ds_write_b16_d16_hi v128, v104 offset:4688
	ds_write_b16 v128, v106 offset:4960
	ds_write_b16_d16_hi v128, v106 offset:5232
	ds_write_b16 v128, v108 offset:6592
	ds_write_b16_d16_hi v128, v108 offset:6864
	ds_write_b16 v128, v110 offset:7136
	ds_write_b16_d16_hi v128, v110 offset:7408
	ds_write_b16 v128, v80 offset:8704
	ds_write_b16_d16_hi v128, v80 offset:8976
	ds_write_b16 v128, v82 offset:9248
	ds_write_b16_d16_hi v128, v82 offset:9520
	ds_write_b16 v128, v84 offset:10880
	ds_write_b16_d16_hi v128, v84 offset:11152
	ds_write_b16 v128, v86 offset:11424
	ds_write_b16_d16_hi v128, v86 offset:11696
	ds_write_b16 v128, v88 offset:13056
	ds_write_b16_d16_hi v128, v88 offset:13328
	ds_write_b16 v128, v90 offset:13600
	ds_write_b16_d16_hi v128, v90 offset:13872
	ds_write_b16 v128, v92 offset:15232
	ds_write_b16_d16_hi v128, v92 offset:15504
	ds_write_b16 v128, v94 offset:15776
	ds_write_b16_d16_hi v128, v94 offset:16048
	ds_write_b16 v128, v64 offset:8768
	ds_write_b16_d16_hi v128, v64 offset:9040
	ds_write_b16 v128, v66 offset:9312
	ds_write_b16_d16_hi v128, v66 offset:9584
	ds_write_b16 v128, v68 offset:10944
	ds_write_b16_d16_hi v128, v68 offset:11216
	ds_write_b16 v128, v70 offset:11488
	ds_write_b16_d16_hi v128, v70 offset:11760
	ds_write_b16 v128, v72 offset:13120
	ds_write_b16_d16_hi v128, v72 offset:13392
	ds_write_b16 v128, v74 offset:13664
	ds_write_b16_d16_hi v128, v74 offset:13936
	ds_write_b16 v128, v76 offset:15296
	ds_write_b16_d16_hi v128, v76 offset:15568
	ds_write_b16 v128, v78 offset:15840
	ds_write_b16_d16_hi v128, v78 offset:16112
	s_waitcnt lgkmcnt(0)
	s_barrier
	ds_read_b128 v[132:135], v129
	ds_read_b128 v[136:139], v129 offset:4352
	ds_read_b128 v[140:143], v129 offset:8704
	ds_read_b128 v[144:147], v129 offset:13056
	ds_read_b128 v[148:151], v129 offset:17408
	ds_read_b128 v[152:155], v129 offset:21760
	ds_read_b128 v[156:159], v129 offset:26112
	ds_read_b128 v[160:163], v129 offset:30464
	v_cvt_pk_bf16_f32 v48, v48, v49
	v_cvt_pk_bf16_f32 v50, v50, v51
	v_cvt_pk_bf16_f32 v52, v52, v53
	v_cvt_pk_bf16_f32 v54, v54, v55
	v_cvt_pk_bf16_f32 v56, v56, v57
	v_cvt_pk_bf16_f32 v58, v58, v59
	v_cvt_pk_bf16_f32 v60, v60, v61
	v_cvt_pk_bf16_f32 v62, v62, v63
	v_cvt_pk_bf16_f32 v32, v32, v33
	v_cvt_pk_bf16_f32 v34, v34, v35
	v_cvt_pk_bf16_f32 v36, v36, v37
	v_cvt_pk_bf16_f32 v38, v38, v39
	v_cvt_pk_bf16_f32 v40, v40, v41
	v_cvt_pk_bf16_f32 v42, v42, v43
	v_cvt_pk_bf16_f32 v44, v44, v45
	v_cvt_pk_bf16_f32 v46, v46, v47
	v_cvt_pk_bf16_f32 v16, v16, v17
	v_cvt_pk_bf16_f32 v18, v18, v19
	v_cvt_pk_bf16_f32 v20, v20, v21
	v_cvt_pk_bf16_f32 v22, v22, v23
	v_cvt_pk_bf16_f32 v24, v24, v25
	v_cvt_pk_bf16_f32 v26, v26, v27
	v_cvt_pk_bf16_f32 v28, v28, v29
	v_cvt_pk_bf16_f32 v30, v30, v31
	v_cvt_pk_bf16_f32 v0, v0, v1
	v_cvt_pk_bf16_f32 v2, v2, v3
	v_cvt_pk_bf16_f32 v4, v4, v5
	v_cvt_pk_bf16_f32 v6, v6, v7
	v_cvt_pk_bf16_f32 v8, v8, v9
	v_cvt_pk_bf16_f32 v10, v10, v11
	v_cvt_pk_bf16_f32 v12, v12, v13
	v_cvt_pk_bf16_f32 v14, v14, v15
	s_and_saveexec_b64 s[46:47], s[44:45]
	s_waitcnt lgkmcnt(7)
	global_store_dwordx4 v164, v[132:135], s[42:43]
	s_waitcnt lgkmcnt(6)
	global_store_dwordx4 v165, v[136:139], s[42:43]
	s_waitcnt lgkmcnt(5)
	global_store_dwordx4 v166, v[140:143], s[42:43]
	s_waitcnt lgkmcnt(4)
	global_store_dwordx4 v167, v[144:147], s[42:43]
	s_waitcnt lgkmcnt(3)
	global_store_dwordx4 v168, v[148:151], s[42:43]
	s_waitcnt lgkmcnt(2)
	global_store_dwordx4 v169, v[152:155], s[42:43]
	s_waitcnt lgkmcnt(1)
	global_store_dwordx4 v170, v[156:159], s[42:43]
	s_waitcnt lgkmcnt(0)
	global_store_dwordx4 v171, v[160:163], s[42:43]
	s_or_b64 exec, exec, s[46:47]
	s_barrier
	ds_write_b16 v128, v48
	ds_write_b16_d16_hi v128, v48 offset:272
	ds_write_b16 v128, v50 offset:544
	ds_write_b16_d16_hi v128, v50 offset:816
	ds_write_b16 v128, v52 offset:2176
	ds_write_b16_d16_hi v128, v52 offset:2448
	ds_write_b16 v128, v54 offset:2720
	ds_write_b16_d16_hi v128, v54 offset:2992
	ds_write_b16 v128, v56 offset:4352
	ds_write_b16_d16_hi v128, v56 offset:4624
	ds_write_b16 v128, v58 offset:4896
	ds_write_b16_d16_hi v128, v58 offset:5168
	ds_write_b16 v128, v60 offset:6528
	ds_write_b16_d16_hi v128, v60 offset:6800
	ds_write_b16 v128, v62 offset:7072
	ds_write_b16_d16_hi v128, v62 offset:7344
	ds_write_b16 v128, v32 offset:64
	ds_write_b16_d16_hi v128, v32 offset:336
	ds_write_b16 v128, v34 offset:608
	ds_write_b16_d16_hi v128, v34 offset:880
	ds_write_b16 v128, v36 offset:2240
	ds_write_b16_d16_hi v128, v36 offset:2512
	ds_write_b16 v128, v38 offset:2784
	ds_write_b16_d16_hi v128, v38 offset:3056
	ds_write_b16 v128, v40 offset:4416
	ds_write_b16_d16_hi v128, v40 offset:4688
	ds_write_b16 v128, v42 offset:4960
	ds_write_b16_d16_hi v128, v42 offset:5232
	ds_write_b16 v128, v44 offset:6592
	ds_write_b16_d16_hi v128, v44 offset:6864
	ds_write_b16 v128, v46 offset:7136
	ds_write_b16_d16_hi v128, v46 offset:7408
	ds_write_b16 v128, v16 offset:8704
	ds_write_b16_d16_hi v128, v16 offset:8976
	ds_write_b16 v128, v18 offset:9248
	ds_write_b16_d16_hi v128, v18 offset:9520
	ds_write_b16 v128, v20 offset:10880
	ds_write_b16_d16_hi v128, v20 offset:11152
	ds_write_b16 v128, v22 offset:11424
	ds_write_b16_d16_hi v128, v22 offset:11696
	ds_write_b16 v128, v24 offset:13056
	ds_write_b16_d16_hi v128, v24 offset:13328
	ds_write_b16 v128, v26 offset:13600
	ds_write_b16_d16_hi v128, v26 offset:13872
	ds_write_b16 v128, v28 offset:15232
	ds_write_b16_d16_hi v128, v28 offset:15504
	ds_write_b16 v128, v30 offset:15776
	ds_write_b16_d16_hi v128, v30 offset:16048
	ds_write_b16 v128, v0 offset:8768
	ds_write_b16_d16_hi v128, v0 offset:9040
	ds_write_b16 v128, v2 offset:9312
	ds_write_b16_d16_hi v128, v2 offset:9584
	ds_write_b16 v128, v4 offset:10944
	ds_write_b16_d16_hi v128, v4 offset:11216
	ds_write_b16 v128, v6 offset:11488
	ds_write_b16_d16_hi v128, v6 offset:11760
	ds_write_b16 v128, v8 offset:13120
	ds_write_b16_d16_hi v128, v8 offset:13392
	ds_write_b16 v128, v10 offset:13664
	ds_write_b16_d16_hi v128, v10 offset:13936
	ds_write_b16 v128, v12 offset:15296
	ds_write_b16_d16_hi v128, v12 offset:15568
	ds_write_b16 v128, v14 offset:15840
	ds_write_b16_d16_hi v128, v14 offset:16112
	s_waitcnt lgkmcnt(0)
	s_barrier
	ds_read_b128 v[132:135], v129
	ds_read_b128 v[136:139], v129 offset:4352
	ds_read_b128 v[140:143], v129 offset:8704
	ds_read_b128 v[144:147], v129 offset:13056
	ds_read_b128 v[148:151], v129 offset:17408
	ds_read_b128 v[152:155], v129 offset:21760
	ds_read_b128 v[156:159], v129 offset:26112
	ds_read_b128 v[160:163], v129 offset:30464
	v_add_u32_e32 v164, 0x49000, v164
	v_add_u32_e32 v165, 0x49000, v165
	v_add_u32_e32 v166, 0x49000, v166
	v_add_u32_e32 v167, 0x49000, v167
	v_add_u32_e32 v168, 0x49000, v168
	v_add_u32_e32 v169, 0x49000, v169
	v_add_u32_e32 v170, 0x49000, v170
	v_add_u32_e32 v171, 0x49000, v171
	s_and_saveexec_b64 s[46:47], s[44:45]
	s_waitcnt lgkmcnt(7)
	global_store_dwordx4 v164, v[132:135], s[42:43]
	s_waitcnt lgkmcnt(6)
	global_store_dwordx4 v165, v[136:139], s[42:43]
	s_waitcnt lgkmcnt(5)
	global_store_dwordx4 v166, v[140:143], s[42:43]
	s_waitcnt lgkmcnt(4)
	global_store_dwordx4 v167, v[144:147], s[42:43]
	s_waitcnt lgkmcnt(3)
	global_store_dwordx4 v168, v[148:151], s[42:43]
	s_waitcnt lgkmcnt(2)
	global_store_dwordx4 v169, v[152:155], s[42:43]
	s_waitcnt lgkmcnt(1)
	global_store_dwordx4 v170, v[156:159], s[42:43]
	s_waitcnt lgkmcnt(0)
	global_store_dwordx4 v171, v[160:163], s[42:43]
	s_or_b64 exec, exec, s[46:47]
	s_branch .LBB0_1281

.LBB0_1977:
	ds_read_b128 v[216:219], v188 offset:36864
	ds_read_b128 v[200:203], v187
	ds_read_b128 v[220:223], v188 offset:41472
	ds_read_b128 v[204:207], v187 offset:4608
	ds_read_b128 v[208:211], v187 offset:9216
	ds_read_b128 v[212:215], v176
	s_waitcnt lgkmcnt(4)
	v_mfma_f32_32x32x16_bf16 v[112:127], v[200:203], v[216:219], v[112:127]
	ds_read_b128 v[240:243], v188 offset:36896
	global_load_dwordx4 v[160:163], v190, s[38:39]
	s_waitcnt lgkmcnt(4)
	v_mfma_f32_32x32x16_bf16 v[96:111], v[200:203], v[220:223], v[96:111]
	ds_read_b128 v[224:227], v187 offset:32
	global_load_dwordx4 v[128:131], v191, s[38:39]
	s_waitcnt lgkmcnt(4)
	v_mfma_f32_32x32x16_bf16 v[80:95], v[204:207], v[216:219], v[80:95]
	ds_read_b128 v[244:247], v188 offset:41504
	global_load_dwordx4 v[132:135], v192, s[38:39]
	s_waitcnt lgkmcnt(5)
	v_mfma_f32_32x32x16_bf16 v[64:79], v[204:207], v[220:223], v[64:79]
	ds_read_b128 v[228:231], v187 offset:4640
	global_load_dwordx4 v[136:139], v193, s[38:39]
	s_waitcnt lgkmcnt(5)
	v_mfma_f32_32x32x16_bf16 v[48:63], v[208:211], v[216:219], v[48:63]
	ds_read_b128 v[232:235], v187 offset:9248
	global_load_dwordx4 v[140:143], v194, s[38:39]
	s_waitcnt lgkmcnt(6)
	v_mfma_f32_32x32x16_bf16 v[32:47], v[208:211], v[220:223], v[32:47]
	ds_read_b128 v[236:239], v176 offset:32
	global_load_dwordx4 v[144:147], v195, s[38:39]
	s_waitcnt lgkmcnt(6)
	v_mfma_f32_32x32x16_bf16 v[16:31], v[212:215], v[216:219], v[16:31]
	global_load_dwordx4 v[148:151], v196, s[38:39]
	s_waitcnt lgkmcnt(6)
	v_mfma_f32_32x32x16_bf16 v[0:15], v[212:215], v[220:223], v[0:15]
	global_load_dwordx4 v[156:159], v197, s[38:39]
	s_waitcnt lgkmcnt(4)
	v_mfma_f32_32x32x16_bf16 v[112:127], v[224:227], v[240:243], v[112:127]
	ds_read_b128 v[200:203], v187 offset:64
	global_load_dwordx4 v[152:155], v190, s[40:41]
	s_waitcnt lgkmcnt(4)
	v_mfma_f32_32x32x16_bf16 v[96:111], v[224:227], v[244:247], v[96:111]
	ds_read_b128 v[204:207], v187 offset:4672
	global_load_dwordx4 v[164:167], v191, s[40:41]
	s_waitcnt lgkmcnt(4)
	v_mfma_f32_32x32x16_bf16 v[80:95], v[228:231], v[240:243], v[80:95]
	ds_read_b128 v[208:211], v187 offset:9280
	global_load_dwordx4 v[168:171], v192, s[40:41]
	s_waitcnt lgkmcnt(5)
	v_mfma_f32_32x32x16_bf16 v[64:79], v[228:231], v[244:247], v[64:79]
	ds_read_b128 v[212:215], v176 offset:64
	global_load_dwordx4 v[172:175], v193, s[40:41]
	s_add_u32 s38, s38, 0x80
	s_addc_u32 s39, s39, 0
	s_add_u32 s40, s40, 0x80
	s_addc_u32 s41, s41, 0
	s_add_u32 s12, s12, 0x80
	s_waitcnt lgkmcnt(5)
	v_mfma_f32_32x32x16_bf16 v[48:63], v[232:235], v[240:243], v[48:63]
	ds_read_b128 v[216:219], v188 offset:36928
	s_waitcnt lgkmcnt(6)
	v_mfma_f32_32x32x16_bf16 v[32:47], v[232:235], v[244:247], v[32:47]
	ds_read_b128 v[220:223], v188 offset:41536
	s_waitcnt lgkmcnt(6)
	v_mfma_f32_32x32x16_bf16 v[16:31], v[236:239], v[240:243], v[16:31]
	s_waitcnt lgkmcnt(6)
	v_mfma_f32_32x32x16_bf16 v[0:15], v[236:239], v[244:247], v[0:15]
	s_waitcnt lgkmcnt(1)
	v_mfma_f32_32x32x16_bf16 v[112:127], v[200:203], v[216:219], v[112:127]
	ds_read_b128 v[224:227], v187 offset:96
	s_waitcnt lgkmcnt(1)
	v_mfma_f32_32x32x16_bf16 v[96:111], v[200:203], v[220:223], v[96:111]
	ds_read_b128 v[228:231], v187 offset:4704
	s_waitcnt lgkmcnt(3)
	v_mfma_f32_32x32x16_bf16 v[80:95], v[204:207], v[216:219], v[80:95]
	ds_read_b128 v[232:235], v187 offset:9312
	s_waitcnt lgkmcnt(3)
	v_mfma_f32_32x32x16_bf16 v[64:79], v[204:207], v[220:223], v[64:79]
	ds_read_b128 v[236:239], v176 offset:96
	s_waitcnt lgkmcnt(5)
	v_mfma_f32_32x32x16_bf16 v[48:63], v[208:211], v[216:219], v[48:63]
	ds_read_b128 v[240:243], v188 offset:36960
	s_waitcnt lgkmcnt(5)
	v_mfma_f32_32x32x16_bf16 v[32:47], v[208:211], v[220:223], v[32:47]
	ds_read_b128 v[244:247], v188 offset:41568
	s_waitcnt lgkmcnt(7)
	v_mfma_f32_32x32x16_bf16 v[16:31], v[212:215], v[216:219], v[16:31]
	s_waitcnt lgkmcnt(6)
	v_mfma_f32_32x32x16_bf16 v[0:15], v[212:215], v[220:223], v[0:15]
	s_waitcnt lgkmcnt(0)
	s_barrier
	s_waitcnt vmcnt(0)
	s_waitcnt lgkmcnt(1)
	v_mfma_f32_32x32x16_bf16 v[112:127], v[224:227], v[240:243], v[112:127]
	ds_write_b128 v189, v[160:163]
	ds_write_b128 v189, v[128:131] offset:4608
	s_waitcnt lgkmcnt(2)
	v_mfma_f32_32x32x16_bf16 v[96:111], v[224:227], v[244:247], v[96:111]
	ds_write_b128 v189, v[132:135] offset:9216
	s_waitcnt lgkmcnt(4)
	v_mfma_f32_32x32x16_bf16 v[80:95], v[228:231], v[240:243], v[80:95]
	ds_write_b128 v189, v[136:139] offset:13824
	ds_write_b128 v189, v[140:143] offset:18432
	s_waitcnt lgkmcnt(5)
	v_mfma_f32_32x32x16_bf16 v[64:79], v[228:231], v[244:247], v[64:79]
	ds_write_b128 v189, v[144:147] offset:23040
	s_waitcnt lgkmcnt(7)
	v_mfma_f32_32x32x16_bf16 v[48:63], v[232:235], v[240:243], v[48:63]
	ds_write_b128 v189, v[148:151] offset:27648
	ds_write_b128 v189, v[156:159] offset:32256
	s_waitcnt lgkmcnt(8)
	v_mfma_f32_32x32x16_bf16 v[32:47], v[232:235], v[244:247], v[32:47]
	ds_write_b128 v189, v[152:155] offset:36864
	s_waitcnt lgkmcnt(10)
	v_mfma_f32_32x32x16_bf16 v[16:31], v[236:239], v[240:243], v[16:31]
	ds_write_b128 v189, v[164:167] offset:41472
	ds_write_b128 v189, v[168:171] offset:46080
	s_waitcnt lgkmcnt(11)
	v_mfma_f32_32x32x16_bf16 v[0:15], v[236:239], v[244:247], v[0:15]
	ds_write_b128 v189, v[172:175] offset:50688
	s_waitcnt lgkmcnt(0)
	s_barrier
	s_cmpk_lg_i32 s12, 0x780
	s_cbranch_scc1 .LBB0_1977
	ds_read_b128 v[216:219], v188 offset:36864
	ds_read_b128 v[200:203], v187
	ds_read_b128 v[220:223], v188 offset:41472
	ds_read_b128 v[204:207], v187 offset:4608
	ds_read_b128 v[208:211], v187 offset:9216
	ds_read_b128 v[212:215], v176
	s_waitcnt lgkmcnt(4)
	v_mfma_f32_32x32x16_bf16 v[112:127], v[200:203], v[216:219], v[112:127]
	ds_read_b128 v[240:243], v188 offset:36896
	s_waitcnt lgkmcnt(4)
	v_mfma_f32_32x32x16_bf16 v[96:111], v[200:203], v[220:223], v[96:111]
	ds_read_b128 v[224:227], v187 offset:32
	s_waitcnt lgkmcnt(4)
	v_mfma_f32_32x32x16_bf16 v[80:95], v[204:207], v[216:219], v[80:95]
	ds_read_b128 v[244:247], v188 offset:41504
	s_waitcnt lgkmcnt(5)
	v_mfma_f32_32x32x16_bf16 v[64:79], v[204:207], v[220:223], v[64:79]
	ds_read_b128 v[228:231], v187 offset:4640
	s_waitcnt lgkmcnt(5)
	v_mfma_f32_32x32x16_bf16 v[48:63], v[208:211], v[216:219], v[48:63]
	ds_read_b128 v[232:235], v187 offset:9248
	s_waitcnt lgkmcnt(6)
	v_mfma_f32_32x32x16_bf16 v[32:47], v[208:211], v[220:223], v[32:47]
	ds_read_b128 v[236:239], v176 offset:32
	s_waitcnt lgkmcnt(6)
	v_mfma_f32_32x32x16_bf16 v[16:31], v[212:215], v[216:219], v[16:31]
	s_waitcnt lgkmcnt(6)
	v_mfma_f32_32x32x16_bf16 v[0:15], v[212:215], v[220:223], v[0:15]
	s_waitcnt lgkmcnt(4)
	v_mfma_f32_32x32x16_bf16 v[112:127], v[224:227], v[240:243], v[112:127]
	ds_read_b128 v[200:203], v187 offset:64
	s_waitcnt lgkmcnt(4)
	v_mfma_f32_32x32x16_bf16 v[96:111], v[224:227], v[244:247], v[96:111]
	ds_read_b128 v[204:207], v187 offset:4672
	s_waitcnt lgkmcnt(4)
	v_mfma_f32_32x32x16_bf16 v[80:95], v[228:231], v[240:243], v[80:95]
	ds_read_b128 v[208:211], v187 offset:9280
	s_waitcnt lgkmcnt(5)
	v_mfma_f32_32x32x16_bf16 v[64:79], v[228:231], v[244:247], v[64:79]
	ds_read_b128 v[212:215], v176 offset:64
	s_waitcnt lgkmcnt(5)
	v_mfma_f32_32x32x16_bf16 v[48:63], v[232:235], v[240:243], v[48:63]
	ds_read_b128 v[216:219], v188 offset:36928
	s_waitcnt lgkmcnt(6)
	v_mfma_f32_32x32x16_bf16 v[32:47], v[232:235], v[244:247], v[32:47]
	ds_read_b128 v[220:223], v188 offset:41536
	s_waitcnt lgkmcnt(6)
	v_mfma_f32_32x32x16_bf16 v[16:31], v[236:239], v[240:243], v[16:31]
	s_waitcnt lgkmcnt(6)
	v_mfma_f32_32x32x16_bf16 v[0:15], v[236:239], v[244:247], v[0:15]
	s_waitcnt lgkmcnt(1)
	v_mfma_f32_32x32x16_bf16 v[112:127], v[200:203], v[216:219], v[112:127]
	ds_read_b128 v[224:227], v187 offset:96
	s_waitcnt lgkmcnt(1)
	v_mfma_f32_32x32x16_bf16 v[96:111], v[200:203], v[220:223], v[96:111]
	ds_read_b128 v[228:231], v187 offset:4704
	s_waitcnt lgkmcnt(3)
	v_mfma_f32_32x32x16_bf16 v[80:95], v[204:207], v[216:219], v[80:95]
	ds_read_b128 v[232:235], v187 offset:9312
	s_waitcnt lgkmcnt(3)
	v_mfma_f32_32x32x16_bf16 v[64:79], v[204:207], v[220:223], v[64:79]
	ds_read_b128 v[236:239], v176 offset:96
	s_waitcnt lgkmcnt(5)
	v_mfma_f32_32x32x16_bf16 v[48:63], v[208:211], v[216:219], v[48:63]
	ds_read_b128 v[240:243], v188 offset:36960
	s_waitcnt lgkmcnt(5)
	v_mfma_f32_32x32x16_bf16 v[32:47], v[208:211], v[220:223], v[32:47]
	ds_read_b128 v[244:247], v188 offset:41568
	s_waitcnt lgkmcnt(7)
	v_mfma_f32_32x32x16_bf16 v[16:31], v[212:215], v[216:219], v[16:31]
	s_waitcnt lgkmcnt(6)
	v_mfma_f32_32x32x16_bf16 v[0:15], v[212:215], v[220:223], v[0:15]
	s_waitcnt lgkmcnt(1)
	v_mfma_f32_32x32x16_bf16 v[112:127], v[224:227], v[240:243], v[112:127]
	s_waitcnt lgkmcnt(0)
	v_mfma_f32_32x32x16_bf16 v[96:111], v[224:227], v[244:247], v[96:111]
	s_waitcnt lgkmcnt(1)
	v_mfma_f32_32x32x16_bf16 v[80:95], v[228:231], v[240:243], v[80:95]
	s_waitcnt lgkmcnt(0)
	v_mfma_f32_32x32x16_bf16 v[64:79], v[228:231], v[244:247], v[64:79]
	s_waitcnt lgkmcnt(1)
	v_mfma_f32_32x32x16_bf16 v[48:63], v[232:235], v[240:243], v[48:63]
	s_waitcnt lgkmcnt(0)
	v_mfma_f32_32x32x16_bf16 v[32:47], v[232:235], v[244:247], v[32:47]
	s_waitcnt lgkmcnt(1)
	v_mfma_f32_32x32x16_bf16 v[16:31], v[236:239], v[240:243], v[16:31]
	s_waitcnt lgkmcnt(0)
	v_mfma_f32_32x32x16_bf16 v[0:15], v[236:239], v[244:247], v[0:15]
	s_mul_i32 s42, s6, 0x2000
	s_add_u32 s44, s30, s42
	s_addc_u32 s45, s31, 0
	s_lshl_b32 s42, s58, 1
	s_add_u32 s44, s44, s42
	s_addc_u32 s45, s45, 0
	s_add_u32 s44, s44, 0x7157900
	s_addc_u32 s45, s45, 0
	s_mov_b32 s43, 1
	v_max_f32_e32 v112, 0, v112
	v_max_f32_e32 v113, 0, v113
	v_mul_f32_e32 v112, v112, v112
	v_mul_f32_e32 v113, v113, v113
	v_cvt_pk_bf16_f32 v190, v112, v113
	v_max_f32_e32 v114, 0, v114
	v_max_f32_e32 v115, 0, v115
	v_mul_f32_e32 v114, v114, v114
	v_mul_f32_e32 v115, v115, v115
	v_cvt_pk_bf16_f32 v191, v114, v115
	v_max_f32_e32 v116, 0, v116
	v_max_f32_e32 v117, 0, v117
	v_mul_f32_e32 v116, v116, v116
	v_mul_f32_e32 v117, v117, v117
	v_cvt_pk_bf16_f32 v192, v116, v117
	v_max_f32_e32 v118, 0, v118
	v_max_f32_e32 v119, 0, v119
	v_mul_f32_e32 v118, v118, v118
	v_mul_f32_e32 v119, v119, v119
	v_cvt_pk_bf16_f32 v193, v118, v119
	v_max_f32_e32 v120, 0, v120
	v_max_f32_e32 v121, 0, v121
	v_mul_f32_e32 v120, v120, v120
	v_mul_f32_e32 v121, v121, v121
	v_cvt_pk_bf16_f32 v194, v120, v121
	v_max_f32_e32 v122, 0, v122
	v_max_f32_e32 v123, 0, v123
	v_mul_f32_e32 v122, v122, v122
	v_mul_f32_e32 v123, v123, v123
	v_cvt_pk_bf16_f32 v195, v122, v123
	v_max_f32_e32 v124, 0, v124
	v_max_f32_e32 v125, 0, v125
	v_mul_f32_e32 v124, v124, v124
	v_mul_f32_e32 v125, v125, v125
	v_cvt_pk_bf16_f32 v196, v124, v125
	v_max_f32_e32 v126, 0, v126
	v_max_f32_e32 v127, 0, v127
	v_mul_f32_e32 v126, v126, v126
	v_mul_f32_e32 v127, v127, v127
	v_cvt_pk_bf16_f32 v197, v126, v127
	v_max_f32_e32 v96, 0, v96
	v_max_f32_e32 v97, 0, v97
	v_mul_f32_e32 v96, v96, v96
	v_mul_f32_e32 v97, v97, v97
	v_cvt_pk_bf16_f32 v198, v96, v97
	v_max_f32_e32 v98, 0, v98
	v_max_f32_e32 v99, 0, v99
	v_mul_f32_e32 v98, v98, v98
	v_mul_f32_e32 v99, v99, v99
	v_cvt_pk_bf16_f32 v199, v98, v99
	v_max_f32_e32 v100, 0, v100
	v_max_f32_e32 v101, 0, v101
	v_mul_f32_e32 v100, v100, v100
	v_mul_f32_e32 v101, v101, v101
	v_cvt_pk_bf16_f32 v200, v100, v101
	v_max_f32_e32 v102, 0, v102
	v_max_f32_e32 v103, 0, v103
	v_mul_f32_e32 v102, v102, v102
	v_mul_f32_e32 v103, v103, v103
	v_cvt_pk_bf16_f32 v201, v102, v103
	v_max_f32_e32 v104, 0, v104
	v_max_f32_e32 v105, 0, v105
	v_mul_f32_e32 v104, v104, v104
	v_mul_f32_e32 v105, v105, v105
	v_cvt_pk_bf16_f32 v202, v104, v105
	v_max_f32_e32 v106, 0, v106
	v_max_f32_e32 v107, 0, v107
	v_mul_f32_e32 v106, v106, v106
	v_mul_f32_e32 v107, v107, v107
	v_cvt_pk_bf16_f32 v203, v106, v107
	v_max_f32_e32 v108, 0, v108
	v_max_f32_e32 v109, 0, v109
	v_mul_f32_e32 v108, v108, v108
	v_mul_f32_e32 v109, v109, v109
	v_cvt_pk_bf16_f32 v204, v108, v109
	v_max_f32_e32 v110, 0, v110
	v_max_f32_e32 v111, 0, v111
	v_mul_f32_e32 v110, v110, v110
	v_mul_f32_e32 v111, v111, v111
	v_cvt_pk_bf16_f32 v205, v110, v111
	v_max_f32_e32 v80, 0, v80
	v_max_f32_e32 v81, 0, v81
	v_mul_f32_e32 v80, v80, v80
	v_mul_f32_e32 v81, v81, v81
	v_cvt_pk_bf16_f32 v206, v80, v81
	v_max_f32_e32 v82, 0, v82
	v_max_f32_e32 v83, 0, v83
	v_mul_f32_e32 v82, v82, v82
	v_mul_f32_e32 v83, v83, v83
	v_cvt_pk_bf16_f32 v207, v82, v83
	v_max_f32_e32 v84, 0, v84
	v_max_f32_e32 v85, 0, v85
	v_mul_f32_e32 v84, v84, v84
	v_mul_f32_e32 v85, v85, v85
	v_cvt_pk_bf16_f32 v208, v84, v85
	v_max_f32_e32 v86, 0, v86
	v_max_f32_e32 v87, 0, v87
	v_mul_f32_e32 v86, v86, v86
	v_mul_f32_e32 v87, v87, v87
	v_cvt_pk_bf16_f32 v209, v86, v87
	v_max_f32_e32 v88, 0, v88
	v_max_f32_e32 v89, 0, v89
	v_mul_f32_e32 v88, v88, v88
	v_mul_f32_e32 v89, v89, v89
	v_cvt_pk_bf16_f32 v210, v88, v89
	v_max_f32_e32 v90, 0, v90
	v_max_f32_e32 v91, 0, v91
	v_mul_f32_e32 v90, v90, v90
	v_mul_f32_e32 v91, v91, v91
	v_cvt_pk_bf16_f32 v211, v90, v91
	v_max_f32_e32 v92, 0, v92
	v_max_f32_e32 v93, 0, v93
	v_mul_f32_e32 v92, v92, v92
	v_mul_f32_e32 v93, v93, v93
	v_cvt_pk_bf16_f32 v212, v92, v93
	v_max_f32_e32 v94, 0, v94
	v_max_f32_e32 v95, 0, v95
	v_mul_f32_e32 v94, v94, v94
	v_mul_f32_e32 v95, v95, v95
	v_cvt_pk_bf16_f32 v213, v94, v95
	v_max_f32_e32 v64, 0, v64
	v_max_f32_e32 v65, 0, v65
	v_mul_f32_e32 v64, v64, v64
	v_mul_f32_e32 v65, v65, v65
	v_cvt_pk_bf16_f32 v214, v64, v65
	v_max_f32_e32 v66, 0, v66
	v_max_f32_e32 v67, 0, v67
	v_mul_f32_e32 v66, v66, v66
	v_mul_f32_e32 v67, v67, v67
	v_cvt_pk_bf16_f32 v215, v66, v67
	v_max_f32_e32 v68, 0, v68
	v_max_f32_e32 v69, 0, v69
	v_mul_f32_e32 v68, v68, v68
	v_mul_f32_e32 v69, v69, v69
	v_cvt_pk_bf16_f32 v216, v68, v69
	v_max_f32_e32 v70, 0, v70
	v_max_f32_e32 v71, 0, v71
	v_mul_f32_e32 v70, v70, v70
	v_mul_f32_e32 v71, v71, v71
	v_cvt_pk_bf16_f32 v217, v70, v71
	v_max_f32_e32 v72, 0, v72
	v_max_f32_e32 v73, 0, v73
	v_mul_f32_e32 v72, v72, v72
	v_mul_f32_e32 v73, v73, v73
	v_cvt_pk_bf16_f32 v218, v72, v73
	v_max_f32_e32 v74, 0, v74
	v_max_f32_e32 v75, 0, v75
	v_mul_f32_e32 v74, v74, v74
	v_mul_f32_e32 v75, v75, v75
	v_cvt_pk_bf16_f32 v219, v74, v75
	v_max_f32_e32 v76, 0, v76
	v_max_f32_e32 v77, 0, v77
	v_mul_f32_e32 v76, v76, v76
	v_mul_f32_e32 v77, v77, v77
	v_cvt_pk_bf16_f32 v220, v76, v77
	v_max_f32_e32 v78, 0, v78
	v_max_f32_e32 v79, 0, v79
	v_mul_f32_e32 v78, v78, v78
	v_mul_f32_e32 v79, v79, v79
	v_cvt_pk_bf16_f32 v221, v78, v79
	v_max_f32_e32 v48, 0, v48
	v_max_f32_e32 v49, 0, v49
	v_mul_f32_e32 v48, v48, v48
	v_mul_f32_e32 v49, v49, v49
	v_cvt_pk_bf16_f32 v222, v48, v49
	v_max_f32_e32 v50, 0, v50
	v_max_f32_e32 v51, 0, v51
	v_mul_f32_e32 v50, v50, v50
	v_mul_f32_e32 v51, v51, v51
	v_cvt_pk_bf16_f32 v223, v50, v51
	v_max_f32_e32 v52, 0, v52
	v_max_f32_e32 v53, 0, v53
	v_mul_f32_e32 v52, v52, v52
	v_mul_f32_e32 v53, v53, v53
	v_cvt_pk_bf16_f32 v224, v52, v53
	v_max_f32_e32 v54, 0, v54
	v_max_f32_e32 v55, 0, v55
	v_mul_f32_e32 v54, v54, v54
	v_mul_f32_e32 v55, v55, v55
	v_cvt_pk_bf16_f32 v225, v54, v55
	v_max_f32_e32 v56, 0, v56
	v_max_f32_e32 v57, 0, v57
	v_mul_f32_e32 v56, v56, v56
	v_mul_f32_e32 v57, v57, v57
	v_cvt_pk_bf16_f32 v226, v56, v57
	v_max_f32_e32 v58, 0, v58
	v_max_f32_e32 v59, 0, v59
	v_mul_f32_e32 v58, v58, v58
	v_mul_f32_e32 v59, v59, v59
	v_cvt_pk_bf16_f32 v227, v58, v59
	v_max_f32_e32 v60, 0, v60
	v_max_f32_e32 v61, 0, v61
	v_mul_f32_e32 v60, v60, v60
	v_mul_f32_e32 v61, v61, v61
	v_cvt_pk_bf16_f32 v228, v60, v61
	v_max_f32_e32 v62, 0, v62
	v_max_f32_e32 v63, 0, v63
	v_mul_f32_e32 v62, v62, v62
	v_mul_f32_e32 v63, v63, v63
	v_cvt_pk_bf16_f32 v229, v62, v63
	v_max_f32_e32 v32, 0, v32
	v_max_f32_e32 v33, 0, v33
	v_mul_f32_e32 v32, v32, v32
	v_mul_f32_e32 v33, v33, v33
	v_cvt_pk_bf16_f32 v230, v32, v33
	v_max_f32_e32 v34, 0, v34
	v_max_f32_e32 v35, 0, v35
	v_mul_f32_e32 v34, v34, v34
	v_mul_f32_e32 v35, v35, v35
	v_cvt_pk_bf16_f32 v231, v34, v35
	v_max_f32_e32 v36, 0, v36
	v_max_f32_e32 v37, 0, v37
	v_mul_f32_e32 v36, v36, v36
	v_mul_f32_e32 v37, v37, v37
	v_cvt_pk_bf16_f32 v232, v36, v37
	v_max_f32_e32 v38, 0, v38
	v_max_f32_e32 v39, 0, v39
	v_mul_f32_e32 v38, v38, v38
	v_mul_f32_e32 v39, v39, v39
	v_cvt_pk_bf16_f32 v233, v38, v39
	v_max_f32_e32 v40, 0, v40
	v_max_f32_e32 v41, 0, v41
	v_mul_f32_e32 v40, v40, v40
	v_mul_f32_e32 v41, v41, v41
	v_cvt_pk_bf16_f32 v234, v40, v41
	v_max_f32_e32 v42, 0, v42
	v_max_f32_e32 v43, 0, v43
	v_mul_f32_e32 v42, v42, v42
	v_mul_f32_e32 v43, v43, v43
	v_cvt_pk_bf16_f32 v235, v42, v43
	v_max_f32_e32 v44, 0, v44
	v_max_f32_e32 v45, 0, v45
	v_mul_f32_e32 v44, v44, v44
	v_mul_f32_e32 v45, v45, v45
	v_cvt_pk_bf16_f32 v236, v44, v45
	v_max_f32_e32 v46, 0, v46
	v_max_f32_e32 v47, 0, v47
	v_mul_f32_e32 v46, v46, v46
	v_mul_f32_e32 v47, v47, v47
	v_cvt_pk_bf16_f32 v237, v46, v47
	v_max_f32_e32 v16, 0, v16
	v_max_f32_e32 v17, 0, v17
	v_mul_f32_e32 v16, v16, v16
	v_mul_f32_e32 v17, v17, v17
	v_cvt_pk_bf16_f32 v238, v16, v17
	v_max_f32_e32 v18, 0, v18
	v_max_f32_e32 v19, 0, v19
	v_mul_f32_e32 v18, v18, v18
	v_mul_f32_e32 v19, v19, v19
	v_cvt_pk_bf16_f32 v239, v18, v19
	v_max_f32_e32 v20, 0, v20
	v_max_f32_e32 v21, 0, v21
	v_mul_f32_e32 v20, v20, v20
	v_mul_f32_e32 v21, v21, v21
	v_cvt_pk_bf16_f32 v240, v20, v21
	v_max_f32_e32 v22, 0, v22
	v_max_f32_e32 v23, 0, v23
	v_mul_f32_e32 v22, v22, v22
	v_mul_f32_e32 v23, v23, v23
	v_cvt_pk_bf16_f32 v241, v22, v23
	v_max_f32_e32 v24, 0, v24
	v_max_f32_e32 v25, 0, v25
	v_mul_f32_e32 v24, v24, v24
	v_mul_f32_e32 v25, v25, v25
	v_cvt_pk_bf16_f32 v242, v24, v25
	v_max_f32_e32 v26, 0, v26
	v_max_f32_e32 v27, 0, v27
	v_mul_f32_e32 v26, v26, v26
	v_mul_f32_e32 v27, v27, v27
	v_cvt_pk_bf16_f32 v243, v26, v27
	v_max_f32_e32 v28, 0, v28
	v_max_f32_e32 v29, 0, v29
	v_mul_f32_e32 v28, v28, v28
	v_mul_f32_e32 v29, v29, v29
	v_cvt_pk_bf16_f32 v244, v28, v29
	v_max_f32_e32 v30, 0, v30
	v_max_f32_e32 v31, 0, v31
	v_mul_f32_e32 v30, v30, v30
	v_mul_f32_e32 v31, v31, v31
	v_cvt_pk_bf16_f32 v245, v30, v31
	v_max_f32_e32 v0, 0, v0
	v_max_f32_e32 v1, 0, v1
	v_mul_f32_e32 v0, v0, v0
	v_mul_f32_e32 v1, v1, v1
	v_cvt_pk_bf16_f32 v246, v0, v1
	v_max_f32_e32 v2, 0, v2
	v_max_f32_e32 v3, 0, v3
	v_mul_f32_e32 v2, v2, v2
	v_mul_f32_e32 v3, v3, v3
	v_cvt_pk_bf16_f32 v247, v2, v3
	v_max_f32_e32 v4, 0, v4
	v_max_f32_e32 v5, 0, v5
	v_mul_f32_e32 v4, v4, v4
	v_mul_f32_e32 v5, v5, v5
	v_cvt_pk_bf16_f32 v248, v4, v5
	v_max_f32_e32 v6, 0, v6
	v_max_f32_e32 v7, 0, v7
	v_mul_f32_e32 v6, v6, v6
	v_mul_f32_e32 v7, v7, v7
	v_cvt_pk_bf16_f32 v249, v6, v7
	v_max_f32_e32 v8, 0, v8
	v_max_f32_e32 v9, 0, v9
	v_mul_f32_e32 v8, v8, v8
	v_mul_f32_e32 v9, v9, v9
	v_cvt_pk_bf16_f32 v250, v8, v9
	v_max_f32_e32 v10, 0, v10
	v_max_f32_e32 v11, 0, v11
	v_mul_f32_e32 v10, v10, v10
	v_mul_f32_e32 v11, v11, v11
	v_cvt_pk_bf16_f32 v251, v10, v11
	v_max_f32_e32 v12, 0, v12
	v_max_f32_e32 v13, 0, v13
	v_mul_f32_e32 v12, v12, v12
	v_mul_f32_e32 v13, v13, v13
	v_cvt_pk_bf16_f32 v252, v12, v13
	v_max_f32_e32 v14, 0, v14
	v_max_f32_e32 v15, 0, v15
	v_mul_f32_e32 v14, v14, v14
	v_mul_f32_e32 v15, v15, v15
	v_cvt_pk_bf16_f32 v253, v14, v15
	s_add_i32 s57, s57, s21
	s_add_i32 s56, s56, s21
	s_cmpk_lt_u32 s57, 0x200
	s_cbranch_scc1 .LBB0_1976
	v_and_b32_e32 v3, 15, v182
	v_lshrrev_b32_e32 v4, 4, v182
	v_mul_u32_u24_e32 v2, 0x2000, v4
	v_lshl_add_u32 v2, v3, 4, v2
	v_mul_u32_u24_e32 v1, 0x110, v4
	v_lshl_add_u32 v1, v3, 4, v1
	v_lshrrev_b32_e32 v3, 7, v182
	v_bfe_u32 v4, v182, 5, 1
	v_lshlrev_b32_e32 v3, 6, v3
	v_lshl_or_b32 v3, v4, 2, v3
	v_mul_u32_u24_e32 v3, 136, v3
	v_and_b32_e32 v4, 0x5f, v182
	v_add_lshl_u32 v0, v3, v4, 1
	s_barrier
	ds_write_b16 v0, v190
	ds_write_b16_d16_hi v0, v190 offset:272
	ds_write_b16 v0, v191 offset:544
	ds_write_b16_d16_hi v0, v191 offset:816
	ds_write_b16 v0, v192 offset:2176
	ds_write_b16_d16_hi v0, v192 offset:2448
	ds_write_b16 v0, v193 offset:2720
	ds_write_b16_d16_hi v0, v193 offset:2992
	ds_write_b16 v0, v194 offset:4352
	ds_write_b16_d16_hi v0, v194 offset:4624
	ds_write_b16 v0, v195 offset:4896
	ds_write_b16_d16_hi v0, v195 offset:5168
	ds_write_b16 v0, v196 offset:6528
	ds_write_b16_d16_hi v0, v196 offset:6800
	ds_write_b16 v0, v197 offset:7072
	ds_write_b16_d16_hi v0, v197 offset:7344
	ds_write_b16 v0, v198 offset:64
	ds_write_b16_d16_hi v0, v198 offset:336
	ds_write_b16 v0, v199 offset:608
	ds_write_b16_d16_hi v0, v199 offset:880
	ds_write_b16 v0, v200 offset:2240
	ds_write_b16_d16_hi v0, v200 offset:2512
	ds_write_b16 v0, v201 offset:2784
	ds_write_b16_d16_hi v0, v201 offset:3056
	ds_write_b16 v0, v202 offset:4416
	ds_write_b16_d16_hi v0, v202 offset:4688
	ds_write_b16 v0, v203 offset:4960
	ds_write_b16_d16_hi v0, v203 offset:5232
	ds_write_b16 v0, v204 offset:6592
	ds_write_b16_d16_hi v0, v204 offset:6864
	ds_write_b16 v0, v205 offset:7136
	ds_write_b16_d16_hi v0, v205 offset:7408
	ds_write_b16 v0, v206 offset:8704
	ds_write_b16_d16_hi v0, v206 offset:8976
	ds_write_b16 v0, v207 offset:9248
	ds_write_b16_d16_hi v0, v207 offset:9520
	ds_write_b16 v0, v208 offset:10880
	ds_write_b16_d16_hi v0, v208 offset:11152
	ds_write_b16 v0, v209 offset:11424
	ds_write_b16_d16_hi v0, v209 offset:11696
	ds_write_b16 v0, v210 offset:13056
	ds_write_b16_d16_hi v0, v210 offset:13328
	ds_write_b16 v0, v211 offset:13600
	ds_write_b16_d16_hi v0, v211 offset:13872
	ds_write_b16 v0, v212 offset:15232
	ds_write_b16_d16_hi v0, v212 offset:15504
	ds_write_b16 v0, v213 offset:15776
	ds_write_b16_d16_hi v0, v213 offset:16048
	ds_write_b16 v0, v214 offset:8768
	ds_write_b16_d16_hi v0, v214 offset:9040
	ds_write_b16 v0, v215 offset:9312
	ds_write_b16_d16_hi v0, v215 offset:9584
	ds_write_b16 v0, v216 offset:10944
	ds_write_b16_d16_hi v0, v216 offset:11216
	ds_write_b16 v0, v217 offset:11488
	ds_write_b16_d16_hi v0, v217 offset:11760
	ds_write_b16 v0, v218 offset:13120
	ds_write_b16_d16_hi v0, v218 offset:13392
	ds_write_b16 v0, v219 offset:13664
	ds_write_b16_d16_hi v0, v219 offset:13936
	ds_write_b16 v0, v220 offset:15296
	ds_write_b16_d16_hi v0, v220 offset:15568
	ds_write_b16 v0, v221 offset:15840
	ds_write_b16_d16_hi v0, v221 offset:16112
	s_waitcnt lgkmcnt(0)
	s_barrier
	ds_read_b128 v[8:11], v1
	ds_read_b128 v[12:15], v1 offset:4352
	ds_read_b128 v[16:19], v1 offset:8704
	ds_read_b128 v[20:23], v1 offset:13056
	ds_read_b128 v[24:27], v1 offset:17408
	ds_read_b128 v[28:31], v1 offset:21760
	ds_read_b128 v[32:35], v1 offset:26112
	ds_read_b128 v[36:39], v1 offset:30464
	s_add_u32 s38, s44, 0x0
	s_addc_u32 s39, s45, 0
	s_waitcnt lgkmcnt(7)
	global_store_dwordx4 v2, v[8:11], s[38:39]
	s_add_u32 s38, s44, 0x20000
	s_addc_u32 s39, s45, 0
	s_waitcnt lgkmcnt(6)
	global_store_dwordx4 v2, v[12:15], s[38:39]
	s_add_u32 s38, s44, 0x40000
	s_addc_u32 s39, s45, 0
	s_waitcnt lgkmcnt(5)
	global_store_dwordx4 v2, v[16:19], s[38:39]
	s_add_u32 s38, s44, 0x60000
	s_addc_u32 s39, s45, 0
	s_waitcnt lgkmcnt(4)
	global_store_dwordx4 v2, v[20:23], s[38:39]
	s_add_u32 s38, s44, 0x100000
	s_addc_u32 s39, s45, 0
	s_waitcnt lgkmcnt(3)
	global_store_dwordx4 v2, v[24:27], s[38:39]
	s_add_u32 s38, s44, 0x120000
	s_addc_u32 s39, s45, 0
	s_waitcnt lgkmcnt(2)
	global_store_dwordx4 v2, v[28:31], s[38:39]
	s_add_u32 s38, s44, 0x140000
	s_addc_u32 s39, s45, 0
	s_waitcnt lgkmcnt(1)
	global_store_dwordx4 v2, v[32:35], s[38:39]
	s_add_u32 s38, s44, 0x160000
	s_addc_u32 s39, s45, 0
	s_waitcnt lgkmcnt(0)
	global_store_dwordx4 v2, v[36:39], s[38:39]
	s_barrier
	ds_write_b16 v0, v222
	ds_write_b16_d16_hi v0, v222 offset:272
	ds_write_b16 v0, v223 offset:544
	ds_write_b16_d16_hi v0, v223 offset:816
	ds_write_b16 v0, v224 offset:2176
	ds_write_b16_d16_hi v0, v224 offset:2448
	ds_write_b16 v0, v225 offset:2720
	ds_write_b16_d16_hi v0, v225 offset:2992
	ds_write_b16 v0, v226 offset:4352
	ds_write_b16_d16_hi v0, v226 offset:4624
	ds_write_b16 v0, v227 offset:4896
	ds_write_b16_d16_hi v0, v227 offset:5168
	ds_write_b16 v0, v228 offset:6528
	ds_write_b16_d16_hi v0, v228 offset:6800
	ds_write_b16 v0, v229 offset:7072
	ds_write_b16_d16_hi v0, v229 offset:7344
	ds_write_b16 v0, v230 offset:64
	ds_write_b16_d16_hi v0, v230 offset:336
	ds_write_b16 v0, v231 offset:608
	ds_write_b16_d16_hi v0, v231 offset:880
	ds_write_b16 v0, v232 offset:2240
	ds_write_b16_d16_hi v0, v232 offset:2512
	ds_write_b16 v0, v233 offset:2784
	ds_write_b16_d16_hi v0, v233 offset:3056
	ds_write_b16 v0, v234 offset:4416
	ds_write_b16_d16_hi v0, v234 offset:4688
	ds_write_b16 v0, v235 offset:4960
	ds_write_b16_d16_hi v0, v235 offset:5232
	ds_write_b16 v0, v236 offset:6592
	ds_write_b16_d16_hi v0, v236 offset:6864
	ds_write_b16 v0, v237 offset:7136
	ds_write_b16_d16_hi v0, v237 offset:7408
	ds_write_b16 v0, v238 offset:8704
	ds_write_b16_d16_hi v0, v238 offset:8976
	ds_write_b16 v0, v239 offset:9248
	ds_write_b16_d16_hi v0, v239 offset:9520
	ds_write_b16 v0, v240 offset:10880
	ds_write_b16_d16_hi v0, v240 offset:11152
	ds_write_b16 v0, v241 offset:11424
	ds_write_b16_d16_hi v0, v241 offset:11696
	ds_write_b16 v0, v242 offset:13056
	ds_write_b16_d16_hi v0, v242 offset:13328
	ds_write_b16 v0, v243 offset:13600
	ds_write_b16_d16_hi v0, v243 offset:13872
	ds_write_b16 v0, v244 offset:15232
	ds_write_b16_d16_hi v0, v244 offset:15504
	ds_write_b16 v0, v245 offset:15776
	ds_write_b16_d16_hi v0, v245 offset:16048
	ds_write_b16 v0, v246 offset:8768
	ds_write_b16_d16_hi v0, v246 offset:9040
	ds_write_b16 v0, v247 offset:9312
	ds_write_b16_d16_hi v0, v247 offset:9584
	ds_write_b16 v0, v248 offset:10944
	ds_write_b16_d16_hi v0, v248 offset:11216
	ds_write_b16 v0, v249 offset:11488
	ds_write_b16_d16_hi v0, v249 offset:11760
	ds_write_b16 v0, v250 offset:13120
	ds_write_b16_d16_hi v0, v250 offset:13392
	ds_write_b16 v0, v251 offset:13664
	ds_write_b16_d16_hi v0, v251 offset:13936
	ds_write_b16 v0, v252 offset:15296
	ds_write_b16_d16_hi v0, v252 offset:15568
	ds_write_b16 v0, v253 offset:15840
	ds_write_b16_d16_hi v0, v253 offset:16112
	s_waitcnt lgkmcnt(0)
	s_barrier
	ds_read_b128 v[8:11], v1
	ds_read_b128 v[12:15], v1 offset:4352
	ds_read_b128 v[16:19], v1 offset:8704
	ds_read_b128 v[20:23], v1 offset:13056
	ds_read_b128 v[24:27], v1 offset:17408
	ds_read_b128 v[28:31], v1 offset:21760
	ds_read_b128 v[32:35], v1 offset:26112
	ds_read_b128 v[36:39], v1 offset:30464
	s_add_u32 s38, s44, 0x80000
	s_addc_u32 s39, s45, 0
	s_waitcnt lgkmcnt(7)
	global_store_dwordx4 v2, v[8:11], s[38:39]
	s_add_u32 s38, s44, 0xa0000
	s_addc_u32 s39, s45, 0
	s_waitcnt lgkmcnt(6)
	global_store_dwordx4 v2, v[12:15], s[38:39]
	s_add_u32 s38, s44, 0xc0000
	s_addc_u32 s39, s45, 0
	s_waitcnt lgkmcnt(5)
	global_store_dwordx4 v2, v[16:19], s[38:39]
	s_add_u32 s38, s44, 0xe0000
	s_addc_u32 s39, s45, 0
	s_waitcnt lgkmcnt(4)
	global_store_dwordx4 v2, v[20:23], s[38:39]
	s_add_u32 s38, s44, 0x180000
	s_addc_u32 s39, s45, 0
	s_waitcnt lgkmcnt(3)
	global_store_dwordx4 v2, v[24:27], s[38:39]
	s_add_u32 s38, s44, 0x1a0000
	s_addc_u32 s39, s45, 0
	s_waitcnt lgkmcnt(2)
	global_store_dwordx4 v2, v[28:31], s[38:39]
	s_add_u32 s38, s44, 0x1c0000
	s_addc_u32 s39, s45, 0
	s_waitcnt lgkmcnt(1)
	global_store_dwordx4 v2, v[32:35], s[38:39]
	s_add_u32 s38, s44, 0x1e0000
	s_addc_u32 s39, s45, 0
	s_waitcnt lgkmcnt(0)
	global_store_dwordx4 v2, v[36:39], s[38:39]
	s_mov_b32 s43, 0
	s_branch .LBB0_1969
